# static s_setprio 1 for waves 4-7 inside both attention tile loops
# baseline (speedup 1.0000x reference)
; __device__ __forceinline__ unsigned cvt_pk_bf16(float lo, float hi) { f32x2 v = {lo, hi}; bf16x2_t b = __builtin_convertvector(v, bf16x2_t); return __builtin_bit_cast(unsigned, b); }
; template <int DQK, bool MOBA>
; __device__ __forceinline__ void attn_unit(const Args& A, int b, int h, int qb, lptr lds) {
;     ...
;     lrow += __shfl_xor(lrow, 32);
;     const float inv = 1.0f / lrow;
;     bf16* op = A.O + (size_t)qrow * 1024 + h * 128 + 4 * hi;
; #pragma unroll
;     for (int d = 0; d < 4; ++d)
; #pragma unroll
;         for (int a = 0; a < 4; ++a) {
;             u32x2 w; w.x = cvt_pk_bf16(o[d][4 * a] * inv, o[d][4 * a + 1] * inv); w.y = cvt_pk_bf16(o[d][4 * a + 2] * inv, o[d][4 * a + 3] * inv);
;             *(u32x2*)(op + 32 * d + 8 * a) = w;
;         }
.LBB0_755:
	s_setprio 0
	ds_bpermute_b32 v66, v170, v184
	v_readlane_b32 s0, v253, 52
	v_lshlrev_b64 v[64:65], 11, v[160:161]
	v_readlane_b32 s1, v253, 53
	v_lshlrev_b32_e32 v180, 1, v176
	s_waitcnt lgkmcnt(0)
	v_add_f32_e32 v66, v184, v66
	v_lshl_add_u64 v[64:65], s[0:1], 0, v[64:65]
	v_div_scale_f32 v67, s[0:1], v66, v66, 1.0
	v_rcp_f32_e32 v68, v67
	v_div_scale_f32 v69, vcc, 1.0, v66, 1.0
	v_lshl_add_u64 v[64:65], s[46:47], 1, v[64:65]
	v_fma_f32 v70, -v67, v68, 1.0
	v_fmac_f32_e32 v68, v70, v68
	v_mul_f32_e32 v70, v69, v68
	v_fma_f32 v71, -v67, v70, v69
	v_fmac_f32_e32 v70, v71, v68
	v_fma_f32 v67, -v67, v70, v69
	v_div_fmas_f32 v67, v67, v68, v70
	v_div_fixup_f32 v66, v67, v66, 1.0
	v_pk_mul_f32 v[48:49], v[48:49], v[66:67] op_sel_hi:[1,0]
	v_pk_mul_f32 v[50:51], v[50:51], v[66:67] op_sel_hi:[1,0]
	v_pk_mul_f32 v[32:33], v[32:33], v[66:67] op_sel_hi:[1,0]
	v_pk_mul_f32 v[34:35], v[34:35], v[66:67] op_sel_hi:[1,0]
	v_pk_mul_f32 v[16:17], v[16:17], v[66:67] op_sel_hi:[1,0]
	v_pk_mul_f32 v[18:19], v[18:19], v[66:67] op_sel_hi:[1,0]
	v_pk_mul_f32 v[0:1], v[0:1], v[66:67] op_sel_hi:[1,0]
	v_pk_mul_f32 v[2:3], v[2:3], v[66:67] op_sel_hi:[1,0]
	v_lshl_add_u64 v[64:65], v[64:65], 0, v[180:181]
	v_cvt_pk_bf16_f32 v48, v48, v49
	v_cvt_pk_bf16_f32 v49, v50, v51
	v_cvt_pk_bf16_f32 v32, v32, v33
	v_cvt_pk_bf16_f32 v33, v34, v35
	v_cvt_pk_bf16_f32 v16, v16, v17
	v_cvt_pk_bf16_f32 v17, v18, v19
	v_cvt_pk_bf16_f32 v0, v0, v1
	v_cvt_pk_bf16_f32 v1, v2, v3
	global_store_dwordx2 v[64:65], v[48:49], off
	v_pk_mul_f32 v[48:49], v[52:53], v[66:67] op_sel_hi:[1,0]
	v_pk_mul_f32 v[50:51], v[54:55], v[66:67] op_sel_hi:[1,0]
	global_store_dwordx2 v[64:65], v[32:33], off offset:64
	v_pk_mul_f32 v[32:33], v[36:37], v[66:67] op_sel_hi:[1,0]
	v_pk_mul_f32 v[34:35], v[38:39], v[66:67] op_sel_hi:[1,0]
	global_store_dwordx2 v[64:65], v[16:17], off offset:128
	v_pk_mul_f32 v[16:17], v[20:21], v[66:67] op_sel_hi:[1,0]
	v_pk_mul_f32 v[18:19], v[22:23], v[66:67] op_sel_hi:[1,0]
	global_store_dwordx2 v[64:65], v[0:1], off offset:192
	v_pk_mul_f32 v[0:1], v[4:5], v[66:67] op_sel_hi:[1,0]
	v_pk_mul_f32 v[2:3], v[6:7], v[66:67] op_sel_hi:[1,0]
	v_cvt_pk_bf16_f32 v48, v48, v49
	v_cvt_pk_bf16_f32 v49, v50, v51
	v_cvt_pk_bf16_f32 v32, v32, v33
	v_cvt_pk_bf16_f32 v33, v34, v35
	v_cvt_pk_bf16_f32 v16, v16, v17
	v_cvt_pk_bf16_f32 v17, v18, v19
	v_cvt_pk_bf16_f32 v0, v0, v1
	v_cvt_pk_bf16_f32 v1, v2, v3
	global_store_dwordx2 v[64:65], v[48:49], off offset:16
	v_pk_mul_f32 v[48:49], v[56:57], v[66:67] op_sel_hi:[1,0]
	v_pk_mul_f32 v[50:51], v[58:59], v[66:67] op_sel_hi:[1,0]
	global_store_dwordx2 v[64:65], v[32:33], off offset:80
	v_pk_mul_f32 v[32:33], v[40:41], v[66:67] op_sel_hi:[1,0]
	v_pk_mul_f32 v[34:35], v[42:43], v[66:67] op_sel_hi:[1,0]
	global_store_dwordx2 v[64:65], v[16:17], off offset:144
	v_pk_mul_f32 v[16:17], v[24:25], v[66:67] op_sel_hi:[1,0]
	v_pk_mul_f32 v[18:19], v[26:27], v[66:67] op_sel_hi:[1,0]
	global_store_dwordx2 v[64:65], v[0:1], off offset:208
	v_pk_mul_f32 v[0:1], v[8:9], v[66:67] op_sel_hi:[1,0]
	v_pk_mul_f32 v[2:3], v[10:11], v[66:67] op_sel_hi:[1,0]
	v_cvt_pk_bf16_f32 v48, v48, v49
	v_cvt_pk_bf16_f32 v49, v50, v51
	v_cvt_pk_bf16_f32 v32, v32, v33
	v_cvt_pk_bf16_f32 v33, v34, v35
	v_cvt_pk_bf16_f32 v16, v16, v17
	v_cvt_pk_bf16_f32 v17, v18, v19
	v_cvt_pk_bf16_f32 v0, v0, v1
	v_cvt_pk_bf16_f32 v1, v2, v3
	global_store_dwordx2 v[64:65], v[48:49], off offset:32
	v_pk_mul_f32 v[48:49], v[60:61], v[66:67] op_sel_hi:[1,0]
	v_pk_mul_f32 v[50:51], v[62:63], v[66:67] op_sel_hi:[1,0]
	global_store_dwordx2 v[64:65], v[32:33], off offset:96
	v_pk_mul_f32 v[32:33], v[44:45], v[66:67] op_sel_hi:[1,0]
	v_pk_mul_f32 v[34:35], v[46:47], v[66:67] op_sel_hi:[1,0]
	global_store_dwordx2 v[64:65], v[16:17], off offset:160
	v_pk_mul_f32 v[16:17], v[28:29], v[66:67] op_sel_hi:[1,0]
	v_pk_mul_f32 v[18:19], v[30:31], v[66:67] op_sel_hi:[1,0]
	global_store_dwordx2 v[64:65], v[0:1], off offset:224
	v_pk_mul_f32 v[0:1], v[12:13], v[66:67] op_sel_hi:[1,0]
	v_pk_mul_f32 v[2:3], v[14:15], v[66:67] op_sel_hi:[1,0]
	s_add_i32 s53, s53, 1
	v_cvt_pk_bf16_f32 v48, v48, v49
	v_cvt_pk_bf16_f32 v49, v50, v51
	v_cvt_pk_bf16_f32 v32, v32, v33
	v_cvt_pk_bf16_f32 v33, v34, v35
	v_cvt_pk_bf16_f32 v16, v16, v17
	v_cvt_pk_bf16_f32 v17, v18, v19
	v_cvt_pk_bf16_f32 v0, v0, v1
	v_cvt_pk_bf16_f32 v1, v2, v3
	s_cmp_eq_u32 s53, 4
	global_store_dwordx2 v[64:65], v[48:49], off offset:48
	global_store_dwordx2 v[64:65], v[32:33], off offset:112
	global_store_dwordx2 v[64:65], v[16:17], off offset:176
	global_store_dwordx2 v[64:65], v[0:1], off offset:240
	s_cbranch_scc1 .LBB0_753

; template <int DQK, bool MOBA>
; __device__ __forceinline__ void attn_unit(const Args& A, int b, int h, int qb, lptr lds) {
;     ...
;         negm = -(sqrtf(qss * (128.0f * gmx * gmx + 64.0f * grx * grx)) * 1.01f + bmx + 0.01f);
;     }
;     const int NT = 4 * (own + 1);
;     u32x4 kr0, kr1, kr2, vr0, vr1; int pkr = 0;
;     kr2 = (u32x4){0u, 0u, 0u, 0u};
;     ...
;     f32x16 o[4];
; #pragma unroll
;     for (int d = 0; d < 4; ++d)
; #pragma unroll
;         for (int r = 0; r < 16; ++r) o[d][r] = 0.f;
;     float lrow = 0.f;
;     ATT_LOAD(0); ATT_WRITE(0);
;     if (NT > 1) ATT_LOAD(1);
;     __syncthreads();
;     for (int t = 0; t < NT; ++t) {
;         const int buf = t & 1;
;         if (t + 1 < NT) { ATT_WRITE(buf ^ 1); if (t + 2 < NT) ATT_LOAD(t + 2); }
.LBB0_779:
	s_or_b64 exec, exec, s[0:1]
	s_waitcnt lgkmcnt(5)
	v_max_f32_e32 v1, v21, v21
	v_max_f32_e32 v2, v19, v19
	v_max_f32_e32 v1, v2, v1
	v_mul_f32_e32 v3, 0x43000000, v1
	v_add_f32_e32 v0, v16, v17
	v_fma_f32 v1, v1, v3, 0
	v_mul_f32_e32 v0, v0, v1
	v_mul_f32_e32 v1, 0x4f800000, v0
	v_cmp_gt_f32_e32 vcc, s35, v0
	s_waitcnt lgkmcnt(4)
	v_max_f32_e32 v2, v20, v20
	v_max_f32_e32 v3, v18, v18
	v_cndmask_b32_e32 v0, v0, v1, vcc
	v_sqrt_f32_e32 v1, v0
	v_max_f32_e32 v2, v3, v2
	s_lshl_b32 s18, s18, 2
	s_add_i32 s19, s18, 4
	v_add_u32_e32 v3, -1, v1
	v_fma_f32 v4, -v3, v1, v0
	v_cmp_ge_f32_e64 s[0:1], 0, v4
	v_add_u32_e32 v4, 1, v1
	v_lshlrev_b32_e32 v176, 2, v82
	v_cndmask_b32_e64 v3, v1, v3, s[0:1]
	v_fma_f32 v1, -v4, v1, v0
	v_cmp_lt_f32_e64 s[0:1], 0, v1
	v_mov_b32_e32 v48, v181
	v_mov_b32_e32 v49, v181
	v_cndmask_b32_e64 v1, v3, v4, s[0:1]
	v_mul_f32_e32 v3, 0x37800000, v1
	v_cndmask_b32_e32 v1, v1, v3, vcc
	v_cmp_class_f32_e32 vcc, v0, v205
	s_add_i32 s0, 0, 0x12800
	v_lshlrev_b32_e32 v3, 3, v162
	v_cndmask_b32_e32 v0, v1, v0, vcc
	v_mul_u32_u24_e32 v1, 0x110, v83
	v_fmac_f32_e32 v2, 0x3f8147ae, v0
	v_add3_u32 v179, 0, v1, v36
	v_lshrrev_b32_e32 v1, 2, v162
	v_add_f32_e32 v0, 0x3c23d70a, v2
	v_and_or_b32 v1, v1, 3, v176
	v_lshlrev_b32_e32 v2, 1, v162
	s_add_u32 s20, s95, s4
	v_mad_u32_u24 v1, v1, s12, 0
	v_and_b32_e32 v2, 32, v2
	v_and_b32_e32 v3, 24, v3
	s_addc_u32 s21, s8, s5
	v_mul_lo_u32 v174, v22, s12
	v_add3_u32 v183, v1, v2, v3
	v_xor_b32_e32 v64, 0x80000000, v0
	v_bfi_b32 v115, s14, v37, v37
	s_add_u32 s22, s9, s4
	v_add_u32_e32 v185, s0, v36
	v_mov_b32_e32 v50, v181
	v_mov_b32_e32 v51, v181
	v_mov_b32_e32 v52, v181
	v_mov_b32_e32 v53, v181
	v_mov_b32_e32 v54, v181
	v_mov_b32_e32 v55, v181
	v_mov_b32_e32 v56, v181
	v_mov_b32_e32 v57, v181
	v_mov_b32_e32 v58, v181
	v_mov_b32_e32 v59, v181
	v_mov_b32_e32 v60, v181
	v_mov_b32_e32 v61, v181
	v_mov_b32_e32 v62, v181
	v_mov_b32_e32 v63, v181
	v_mov_b64_e32 v[32:33], v[48:49]
	v_mov_b64_e32 v[16:17], v[48:49]
	v_mov_b64_e32 v[0:1], v[48:49]
	v_add_u32_e32 v163, 0x2200, v167
	v_add_u32_e32 v175, 0x2800, v174
	s_mov_b32 s13, 0
	s_mov_b32 s15, 2
	v_or_b32_e32 v177, s71, v83
	v_lshl_add_u32 v178, v162, 2, s0
	v_mov_b32_e32 v65, v64
	v_mov_b32_e32 v66, v64
	v_mov_b32_e32 v67, v64
	v_mov_b32_e32 v68, v64
	v_mov_b32_e32 v69, v64
	v_mov_b32_e32 v70, v64
	v_mov_b32_e32 v71, v64
	v_mov_b32_e32 v72, v64
	v_mov_b32_e32 v73, v64
	v_mov_b32_e32 v74, v64
	v_mov_b32_e32 v75, v64
	v_mov_b32_e32 v76, v64
	v_mov_b32_e32 v77, v64
	v_mov_b32_e32 v78, v64
	v_mov_b32_e32 v79, v64
	v_bfi_b32 v119, s14, v84, v84
	v_bfi_b32 v123, s14, v80, v80
	v_bfi_b32 v127, s14, v81, v81
	v_bfi_b32 v131, s14, v85, v85
	v_bfi_b32 v135, s14, v86, v86
	v_bfi_b32 v139, s14, v87, v87
	v_bfi_b32 v143, s14, v88, v88
	s_addc_u32 s23, s10, s5
	s_addk_i32 s17, 0x100
	v_mov_b32_e32 v184, 0
	v_mov_b64_e32 v[34:35], v[50:51]
	v_mov_b64_e32 v[36:37], v[52:53]
	v_mov_b64_e32 v[38:39], v[54:55]
	v_mov_b64_e32 v[40:41], v[56:57]
	v_mov_b64_e32 v[42:43], v[58:59]
	v_mov_b64_e32 v[44:45], v[60:61]
	v_mov_b64_e32 v[46:47], v[62:63]
	v_mov_b64_e32 v[18:19], v[50:51]
	v_mov_b64_e32 v[20:21], v[52:53]
	v_mov_b64_e32 v[22:23], v[54:55]
	v_mov_b64_e32 v[24:25], v[56:57]
	v_mov_b64_e32 v[26:27], v[58:59]
	v_mov_b64_e32 v[28:29], v[60:61]
	v_mov_b64_e32 v[30:31], v[62:63]
	v_mov_b64_e32 v[2:3], v[50:51]
	v_mov_b64_e32 v[4:5], v[52:53]
	v_mov_b64_e32 v[6:7], v[54:55]
	v_mov_b64_e32 v[8:9], v[56:57]
	v_mov_b64_e32 v[10:11], v[58:59]
	v_mov_b64_e32 v[12:13], v[60:61]
	v_mov_b64_e32 v[14:15], v[62:63]
	s_waitcnt lgkmcnt(0)
	s_barrier
	s_cmp_lt_u32 s71, 0x80
	s_cbranch_scc1 .Lprio_moba
	s_setprio 1
.Lprio_moba:
	s_branch .LBB0_782
.LBB0_780:
	s_add_i32 s0, s15, -1
	s_cmp_ge_u32 s0, s19
	s_cbranch_scc1 .Lmoba_hd_done_a
	s_xor_b32 s4, s24, 1
	s_mul_i32 s0, s4, 0x4400
	s_mul_i32 s1, s4, 0x5000
	v_add3_u32 v232, s0, v167, v166
	s_waitcnt vmcnt(0)
	ds_write_b128 v232, v[144:147]
	v_add3_u32 v232, s0, v163, v166
	ds_write_b128 v232, v[148:151]
	v_add3_u32 v232, s1, v174, v166
	ds_write_b128 v232, v[152:155] offset:34816
	v_add3_u32 v232, s1, v175, v166
	ds_write_b128 v232, v[156:159] offset:34816
	s_and_saveexec_b64 s[0:1], s[40:41]
	v_lshl_add_u32 v232, s4, 8, v178
	v_lshlrev_b32_e32 v173, 2, v173
	ds_write_b32 v232, v173
	s_or_b64 exec, exec, s[0:1]
	s_cmp_ge_u32 s15, s19
	s_cbranch_scc1 .Lmoba_hd_done_a
	s_add_i32 s0, s18, s15
	s_add_i32 s1, s15, -4
	s_add_i32 s6, s15, -2
	s_cmp_lt_u32 s6, 2
	s_cselect_b32 s0, s0, s1
	s_lshl_b32 s4, s0, 6
	s_add_i32 s4, s4, s70
	s_mul_i32 s7, s4, 0x1800
	s_mul_hi_i32 s5, s4, 0x1800
	s_add_u32 s0, s20, s7
	s_addc_u32 s1, s21, s5
	v_lshl_add_u64 v[232:233], s[0:1], 0, v[164:165]
	v_lshl_add_u64 v[234:235], s[0:1], 0, v[168:169]
	s_add_u32 s0, s22, s7
	v_lshl_add_u64 v[232:233], v[232:233], 0, v[180:181]
	s_addc_u32 s1, s23, s5
	v_lshl_add_u64 v[234:235], v[234:235], 0, v[180:181]
	global_load_dwordx4 v[144:147], v[232:233], off
	global_load_dwordx4 v[148:151], v[234:235], off
	v_lshl_add_u64 v[232:233], s[0:1], 0, v[164:165]
	v_lshl_add_u64 v[232:233], v[232:233], 0, v[180:181]
	v_lshl_add_u64 v[234:235], s[0:1], 0, v[168:169]
	v_lshl_add_u64 v[234:235], v[234:235], 0, v[180:181]
	global_load_dwordx4 v[152:155], v[232:233], off
	global_load_dwordx4 v[156:159], v[234:235], off
	s_and_saveexec_b64 s[0:1], s[40:41]
	s_cbranch_execz .Lmoba_hd_pos_a
	v_add_u32_e32 v232, s4, v162
	v_ashrrev_i32_e32 v233, 31, v232
	v_lshl_add_u64 v[232:233], v[232:233], 2, s[54:55]
	global_load_dword v173, v[232:233], off

; __device__ __forceinline__ unsigned cvt_pk_bf16(float lo, float hi) { f32x2 v = {lo, hi}; bf16x2_t b = __builtin_convertvector(v, bf16x2_t); return __builtin_bit_cast(unsigned, b); }
; template <int DQK, bool MOBA>
; __device__ __forceinline__ void attn_unit(const Args& A, int b, int h, int qb, lptr lds) {
;     ...
;         __syncthreads();
;     }
;     lrow += __shfl_xor(lrow, 32);
;     const float inv = 1.0f / lrow;
;     bf16* op = A.O + (size_t)qrow * 1024 + h * 128 + 4 * hi;
; #pragma unroll
;     for (int d = 0; d < 4; ++d)
; #pragma unroll
;         for (int a = 0; a < 4; ++a) {
;             u32x2 w; w.x = cvt_pk_bf16(o[d][4 * a] * inv, o[d][4 * a + 1] * inv); w.y = cvt_pk_bf16(o[d][4 * a + 2] * inv, o[d][4 * a + 3] * inv);
;             *(u32x2*)(op + 32 * d + 8 * a) = w;
;         }
.LBB0_803:
	s_setprio 0
	ds_bpermute_b32 v64, v196, v187
	v_lshlrev_b32_e32 v180, 1, v183
	s_waitcnt lgkmcnt(0)
	s_barrier
	v_add_f32_e32 v64, v187, v64
	v_div_scale_f32 v65, s[0:1], v64, v64, 1.0
	v_rcp_f32_e32 v66, v65
	v_div_scale_f32 v67, vcc, 1.0, v64, 1.0
	v_readlane_b32 s0, v253, 58
	v_fma_f32 v68, -v65, v66, 1.0
	v_fmac_f32_e32 v66, v68, v66
	v_mul_f32_e32 v68, v67, v66
	v_fma_f32 v69, -v65, v68, v67
	v_fmac_f32_e32 v68, v69, v66
	v_fma_f32 v65, -v65, v68, v67
	v_div_fmas_f32 v65, v65, v66, v68
	v_lshlrev_b64 v[66:67], 11, v[184:185]
	v_readlane_b32 s1, v253, 59
	v_div_fixup_f32 v64, v65, v64, 1.0
	v_pk_mul_f32 v[48:49], v[48:49], v[64:65] op_sel_hi:[1,0]
	v_lshl_add_u64 v[66:67], s[0:1], 0, v[66:67]
	v_lshl_add_u64 v[66:67], s[42:43], 1, v[66:67]
	v_pk_mul_f32 v[50:51], v[50:51], v[64:65] op_sel_hi:[1,0]
	v_pk_mul_f32 v[32:33], v[32:33], v[64:65] op_sel_hi:[1,0]
	v_pk_mul_f32 v[34:35], v[34:35], v[64:65] op_sel_hi:[1,0]
	v_pk_mul_f32 v[16:17], v[16:17], v[64:65] op_sel_hi:[1,0]
	v_pk_mul_f32 v[18:19], v[18:19], v[64:65] op_sel_hi:[1,0]
	v_pk_mul_f32 v[0:1], v[0:1], v[64:65] op_sel_hi:[1,0]
	v_pk_mul_f32 v[2:3], v[2:3], v[64:65] op_sel_hi:[1,0]
	v_lshl_add_u64 v[66:67], v[66:67], 0, v[180:181]
	v_cvt_pk_bf16_f32 v48, v48, v49
	v_cvt_pk_bf16_f32 v49, v50, v51
	v_cvt_pk_bf16_f32 v32, v32, v33
	v_cvt_pk_bf16_f32 v33, v34, v35
	v_cvt_pk_bf16_f32 v16, v16, v17
	v_cvt_pk_bf16_f32 v17, v18, v19
	v_cvt_pk_bf16_f32 v0, v0, v1
	v_cvt_pk_bf16_f32 v1, v2, v3
	global_store_dwordx2 v[66:67], v[48:49], off
	v_pk_mul_f32 v[48:49], v[52:53], v[64:65] op_sel_hi:[1,0]
	v_pk_mul_f32 v[50:51], v[54:55], v[64:65] op_sel_hi:[1,0]
	global_store_dwordx2 v[66:67], v[32:33], off offset:64
	v_pk_mul_f32 v[32:33], v[36:37], v[64:65] op_sel_hi:[1,0]
	v_pk_mul_f32 v[34:35], v[38:39], v[64:65] op_sel_hi:[1,0]
	global_store_dwordx2 v[66:67], v[16:17], off offset:128
	v_pk_mul_f32 v[16:17], v[20:21], v[64:65] op_sel_hi:[1,0]
	v_pk_mul_f32 v[18:19], v[22:23], v[64:65] op_sel_hi:[1,0]
	global_store_dwordx2 v[66:67], v[0:1], off offset:192
	v_pk_mul_f32 v[0:1], v[4:5], v[64:65] op_sel_hi:[1,0]
	v_pk_mul_f32 v[2:3], v[6:7], v[64:65] op_sel_hi:[1,0]
	v_cvt_pk_bf16_f32 v48, v48, v49
	v_cvt_pk_bf16_f32 v49, v50, v51
	v_cvt_pk_bf16_f32 v32, v32, v33
	v_cvt_pk_bf16_f32 v33, v34, v35
	v_cvt_pk_bf16_f32 v16, v16, v17
	v_cvt_pk_bf16_f32 v17, v18, v19
	v_cvt_pk_bf16_f32 v0, v0, v1
	v_cvt_pk_bf16_f32 v1, v2, v3
	global_store_dwordx2 v[66:67], v[48:49], off offset:16
	v_pk_mul_f32 v[48:49], v[56:57], v[64:65] op_sel_hi:[1,0]
	v_pk_mul_f32 v[50:51], v[58:59], v[64:65] op_sel_hi:[1,0]
	global_store_dwordx2 v[66:67], v[32:33], off offset:80
	v_pk_mul_f32 v[32:33], v[40:41], v[64:65] op_sel_hi:[1,0]
	v_pk_mul_f32 v[34:35], v[42:43], v[64:65] op_sel_hi:[1,0]
	global_store_dwordx2 v[66:67], v[16:17], off offset:144
	v_pk_mul_f32 v[16:17], v[24:25], v[64:65] op_sel_hi:[1,0]
	v_pk_mul_f32 v[18:19], v[26:27], v[64:65] op_sel_hi:[1,0]
	global_store_dwordx2 v[66:67], v[0:1], off offset:208
	v_pk_mul_f32 v[0:1], v[8:9], v[64:65] op_sel_hi:[1,0]
	v_pk_mul_f32 v[2:3], v[10:11], v[64:65] op_sel_hi:[1,0]
	v_cvt_pk_bf16_f32 v48, v48, v49
	v_cvt_pk_bf16_f32 v49, v50, v51
	v_cvt_pk_bf16_f32 v32, v32, v33
	v_cvt_pk_bf16_f32 v33, v34, v35
	v_cvt_pk_bf16_f32 v16, v16, v17
	v_cvt_pk_bf16_f32 v17, v18, v19
	v_cvt_pk_bf16_f32 v0, v0, v1
	v_cvt_pk_bf16_f32 v1, v2, v3
	global_store_dwordx2 v[66:67], v[48:49], off offset:32
	v_pk_mul_f32 v[48:49], v[60:61], v[64:65] op_sel_hi:[1,0]
	v_pk_mul_f32 v[50:51], v[62:63], v[64:65] op_sel_hi:[1,0]
	global_store_dwordx2 v[66:67], v[32:33], off offset:96
	v_pk_mul_f32 v[32:33], v[44:45], v[64:65] op_sel_hi:[1,0]
	v_pk_mul_f32 v[34:35], v[46:47], v[64:65] op_sel_hi:[1,0]
	global_store_dwordx2 v[66:67], v[16:17], off offset:160
	v_pk_mul_f32 v[16:17], v[28:29], v[64:65] op_sel_hi:[1,0]
	v_pk_mul_f32 v[18:19], v[30:31], v[64:65] op_sel_hi:[1,0]
	global_store_dwordx2 v[66:67], v[0:1], off offset:224
	v_pk_mul_f32 v[0:1], v[12:13], v[64:65] op_sel_hi:[1,0]
	v_pk_mul_f32 v[2:3], v[14:15], v[64:65] op_sel_hi:[1,0]
	s_add_i32 s21, s21, 1
	v_cvt_pk_bf16_f32 v48, v48, v49
	v_cvt_pk_bf16_f32 v49, v50, v51
	v_cvt_pk_bf16_f32 v32, v32, v33
	v_cvt_pk_bf16_f32 v33, v34, v35
	v_cvt_pk_bf16_f32 v16, v16, v17
	v_cvt_pk_bf16_f32 v17, v18, v19
	v_cvt_pk_bf16_f32 v0, v0, v1
	v_cvt_pk_bf16_f32 v1, v2, v3
	s_cmp_eq_u32 s21, 4
	global_store_dwordx2 v[66:67], v[48:49], off offset:48
	global_store_dwordx2 v[66:67], v[32:33], off offset:112
	global_store_dwordx2 v[66:67], v[16:17], off offset:176
	global_store_dwordx2 v[66:67], v[0:1], off offset:240
	s_cbranch_scc1 .LBB0_800

; template <int DQK, bool MOBA>
; __device__ __forceinline__ void attn_unit(const Args& A, int b, int h, int qb, lptr lds) {
;     ...
;     int tid_o = threadIdx.x; asm volatile("" : "+v"(tid_o));
;     const int tid = tid_o, lane = tid & 63, r32 = lane & 31, hi = lane >> 5;
;     const int wid = __builtin_amdgcn_readfirstlane(tid >> 6);
;     const int tb = b * SEQ, q0 = qb * 256, own = qb, bh = b * NH + h;
;     const int qrow = tb + q0 + wid * 32 + r32;
;     const int qrel = wid * 32 + r32;
;     __syncthreads();
;     bf16x8 qf[NS];
;     {
;         const bf16* qp = A.Q + (size_t)qrow * A.q_pitch + h * DQK + 8 * hi;
; #pragma unroll
;         for (int s = 0; s < NS; ++s) qf[s] = *(const bf16x8*)(qp + 16 * s);
.LBB0_809:
	s_lshl_b32 s0, s21, 2
	s_add_i32 s0, s0, s19
	s_ashr_i32 s1, s0, 31
	s_lshr_b32 s1, s1, 29
	s_add_i32 s1, s0, s1
	v_mov_b32_e32 v106, v202
	s_and_b32 s4, s1, -8
	s_lshl_b32 s1, s1, 8
	v_readfirstlane_b32 s5, v106
	s_and_b32 s24, s1, 0xfffff800
	s_lshl_b32 s13, s22, 8
	s_ashr_i32 s15, s5, 1
	s_sub_i32 s0, s0, s4
	s_add_i32 s4, s13, s24
	s_and_b32 s23, s15, 0xffffffe0
	v_and_b32_e32 v108, 31, v106
	s_add_i32 s1, s23, s4
	v_or_b32_e32 v184, s1, v108
	v_mov_b32_e32 v214, 0x20000
	ds_read_b32 v216, v214 offset:80
	v_mov_b32_e32 v217, 0
	s_waitcnt lgkmcnt(0)
	v_lshl_add_u64 v[0:1], s[88:89], 0, v[216:217]
	v_mad_i64_i32 v[0:1], s[6:7], v184, s11, v[0:1]
	s_mul_i32 s6, s0, 0xc0
	v_bfe_u32 v107, v106, 5, 1
	s_ashr_i32 s7, s6, 31
	v_lshl_add_u64 v[0:1], s[6:7], 1, v[0:1]
	v_lshlrev_b32_e32 v180, 4, v107
	v_lshl_add_u64 v[82:83], v[0:1], 0, v[180:181]
	v_and_b32_e32 v76, 32, v106
	s_barrier
	v_lshrrev_b32_e32 v234, 4, v106
	v_add_u32_e32 v234, s4, v234
	v_and_b32_e32 v235, 15, v106
	v_lshlrev_b32_e32 v235, 4, v235
	v_lshl_add_u32 v235, s0, 8, v235
	v_lshl_add_u32 v236, v234, 11, v235
	v_mov_b32_e32 v237, 0
	v_add_u32_e32 v240, 0x10000, v236
	v_mov_b32_e32 v241, 0
	v_lshrrev_b32_e32 v242, 3, v106
	v_add_u32_e32 v242, s4, v242
	v_and_b32_e32 v243, 7, v106
	v_lshlrev_b32_e32 v243, 4, v243
	v_lshl_add_u32 v242, v242, 7, v243
	v_mov_b32_e32 v243, 0
	v_lshl_add_u64 v[238:239], s[90:91], 0, v[236:237]
	v_lshl_add_u64 v[244:245], s[90:91], 0, v[240:241]
	global_load_dwordx4 v[214:217], v[238:239], off
	global_load_dwordx4 v[218:221], v[244:245], off
	v_lshl_add_u64 v[238:239], s[86:87], 0, v[242:243]
	global_load_dwordx4 v[222:225], v[238:239], off
	v_lshl_add_u64 v[244:245], s[92:93], 0, v[240:241]
	v_lshl_add_u64 v[238:239], s[92:93], 0, v[236:237]
	global_load_dwordx4 v[226:229], v[244:245], off
	global_load_dwordx4 v[230:233], v[238:239], off
	global_load_dwordx4 v[84:87], v[82:83], off offset:224
	global_load_dwordx4 v[90:93], v[82:83], off offset:192
	global_load_dwordx4 v[98:101], v[82:83], off offset:160
	global_load_dwordx4 v[68:71], v[82:83], off offset:128
	global_load_dwordx4 v[60:63], v[82:83], off offset:96
	global_load_dwordx4 v[56:59], v[82:83], off offset:64
	global_load_dwordx4 v[48:51], v76, s[28:29] offset:16
	global_load_dwordx4 v[52:55], v76, s[28:29]
	global_load_dwordx4 v[40:43], v76, s[28:29] offset:80
	global_load_dwordx4 v[44:47], v76, s[28:29] offset:64
	global_load_dwordx4 v[32:35], v76, s[28:29] offset:144
	global_load_dwordx4 v[36:39], v76, s[28:29] offset:128
	global_load_dwordx4 v[24:27], v76, s[28:29] offset:208
	global_load_dwordx4 v[28:31], v76, s[28:29] offset:192
	global_load_dwordx4 v[64:67], v[82:83], off
	global_load_dwordx4 v[112:115], v[82:83], off offset:32
	global_load_dwordx4 v[16:19], v76, s[28:29] offset:272
	global_load_dwordx4 v[20:23], v76, s[28:29] offset:256
	global_load_dwordx4 v[8:11], v76, s[28:29] offset:336
	global_load_dwordx4 v[12:15], v76, s[28:29] offset:320
	v_and_b32_e32 v1, 64, v206
	v_xor_b32_e32 v0, 32, v206
	v_add_u32_e32 v109, 64, v1
	v_cmp_lt_i32_e32 vcc, v0, v109
	v_ashrrev_i32_e32 v185, 31, v184
	v_mov_b32_e32 v77, v181
	v_cndmask_b32_e32 v0, v206, v0, vcc
	v_lshlrev_b32_e32 v196, 2, v0
	global_load_dwordx4 v[0:3], v[82:83], off offset:256
	global_load_dwordx4 v[4:7], v[82:83], off offset:288
	v_and_b32_e32 v110, 63, v106
	s_lshl_b32 s25, s22, 2
	s_ashr_i32 s5, s4, 31
	s_add_i32 s26, s25, 4
	s_lshl_b64 s[44:45], s[4:5], 11
	s_add_u32 s1, s90, s44
	s_addc_u32 s5, s91, s45
	s_lshl_b32 s42, s0, 7
	s_ashr_i32 s43, s42, 31
	s_lshl_b64 s[6:7], s[42:43], 1
	s_add_u32 s0, s1, s6
	s_addc_u32 s1, s5, s7
	s_mov_b32 s5, 2
	s_mov_b32 s27, 0
	s_waitcnt vmcnt(21)
	v_and_b32_e32 v73, 0xffff0000, v87
	s_waitcnt vmcnt(7)
	v_and_b32_e32 v201, 0xffff0000, v64
	v_lshlrev_b32_e32 v200, 16, v64
	v_and_b32_e32 v195, 0xffff0000, v65
	v_lshlrev_b32_e32 v194, 16, v65
	v_pk_mul_f32 v[64:65], v[200:201], v[200:201]
	v_pk_mul_f32 v[198:199], v[194:195], v[194:195]
	v_add_f32_e32 v64, v64, v65
	v_and_b32_e32 v193, 0xffff0000, v66
	v_lshlrev_b32_e32 v192, 16, v66
	v_add_f32_e32 v64, v198, v64
	v_and_b32_e32 v189, 0xffff0000, v67
	v_lshlrev_b32_e32 v188, 16, v67
	v_pk_mul_f32 v[66:67], v[192:193], v[192:193]
	v_add_f32_e32 v64, v199, v64
	v_add_f32_e32 v64, v66, v64
	v_pk_mul_f32 v[190:191], v[188:189], v[188:189]
	v_add_f32_e32 v64, v67, v64
	s_waitcnt vmcnt(6)
; __device__ __forceinline__ float bf2f(unsigned short v) { return __uint_as_float(((unsigned)v) << 16); }
; template <int DQK, bool MOBA>
; __device__ __forceinline__ void attn_unit(const Args& A, int b, int h, int qb, lptr lds) {
;     ...
;     {
;         float ssn = 0.f;
; #pragma unroll
;         for (int s = 0; s < 8; ++s)
; #pragma unroll
;             for (int e = 0; e < 8; ++e) { const float f = bf2f((unsigned short)qf[s][e]); ssn += f * f; }
;         ssn += __shfl_xor(ssn, 32);
	v_and_b32_e32 v187, 0xffff0000, v112
	v_lshlrev_b32_e32 v186, 16, v112
	v_add_f32_e32 v64, v190, v64
	v_and_b32_e32 v177, 0xffff0000, v113
	v_lshlrev_b32_e32 v176, 16, v113
	v_pk_mul_f32 v[112:113], v[186:187], v[186:187]
	v_add_f32_e32 v64, v191, v64
	v_add_f32_e32 v64, v112, v64
	v_pk_mul_f32 v[178:179], v[176:177], v[176:177]
	v_add_f32_e32 v64, v113, v64
	v_and_b32_e32 v175, 0xffff0000, v114
	v_lshlrev_b32_e32 v174, 16, v114
	v_add_f32_e32 v64, v178, v64
	v_and_b32_e32 v171, 0xffff0000, v115
	v_lshlrev_b32_e32 v170, 16, v115
	v_pk_mul_f32 v[114:115], v[174:175], v[174:175]
	v_add_f32_e32 v64, v179, v64
	v_add_f32_e32 v64, v114, v64
	v_pk_mul_f32 v[172:173], v[170:171], v[170:171]
	v_add_f32_e32 v64, v115, v64
	v_and_b32_e32 v169, 0xffff0000, v56
	v_lshlrev_b32_e32 v168, 16, v56
	v_add_f32_e32 v64, v172, v64
	v_and_b32_e32 v165, 0xffff0000, v57
	v_lshlrev_b32_e32 v164, 16, v57
	v_pk_mul_f32 v[56:57], v[168:169], v[168:169]
	v_add_f32_e32 v64, v173, v64
	v_add_f32_e32 v56, v56, v64
	v_pk_mul_f32 v[166:167], v[164:165], v[164:165]
	v_add_f32_e32 v56, v57, v56
	v_and_b32_e32 v163, 0xffff0000, v58
	v_lshlrev_b32_e32 v162, 16, v58
	v_add_f32_e32 v56, v166, v56
	v_and_b32_e32 v159, 0xffff0000, v59
	v_lshlrev_b32_e32 v158, 16, v59
	v_pk_mul_f32 v[58:59], v[162:163], v[162:163]
	v_add_f32_e32 v56, v167, v56
	v_add_f32_e32 v56, v58, v56
	v_pk_mul_f32 v[160:161], v[158:159], v[158:159]
	v_add_f32_e32 v56, v59, v56
	v_and_b32_e32 v157, 0xffff0000, v60
	v_lshlrev_b32_e32 v156, 16, v60
	v_add_f32_e32 v56, v160, v56
	v_and_b32_e32 v155, 0xffff0000, v61
	v_lshlrev_b32_e32 v154, 16, v61
	v_pk_mul_f32 v[60:61], v[156:157], v[156:157]
	v_add_f32_e32 v56, v161, v56
	v_add_f32_e32 v56, v60, v56
	v_pk_mul_f32 v[148:149], v[154:155], v[154:155]
	v_add_f32_e32 v56, v61, v56
	v_and_b32_e32 v153, 0xffff0000, v62
	v_lshlrev_b32_e32 v152, 16, v62
	v_add_f32_e32 v56, v148, v56
	v_and_b32_e32 v151, 0xffff0000, v63
	v_lshlrev_b32_e32 v150, 16, v63
	v_pk_mul_f32 v[62:63], v[152:153], v[152:153]
	v_add_f32_e32 v56, v149, v56
	v_add_f32_e32 v56, v62, v56
	v_pk_mul_f32 v[146:147], v[150:151], v[150:151]
	v_add_f32_e32 v56, v63, v56
	v_and_b32_e32 v105, 0xffff0000, v68
	v_lshlrev_b32_e32 v104, 16, v68
	v_add_f32_e32 v56, v146, v56
	v_and_b32_e32 v103, 0xffff0000, v69
	v_lshlrev_b32_e32 v102, 16, v69
	v_pk_mul_f32 v[68:69], v[104:105], v[104:105]
	v_add_f32_e32 v56, v147, v56
	v_add_f32_e32 v56, v68, v56
	v_pk_mul_f32 v[144:145], v[102:103], v[102:103]
	v_add_f32_e32 v56, v69, v56
	v_lshlrev_b32_e32 v72, 16, v87
	v_and_b32_e32 v75, 0xffff0000, v86
	v_lshlrev_b32_e32 v74, 16, v86
	v_and_b32_e32 v79, 0xffff0000, v85
	v_lshlrev_b32_e32 v78, 16, v85
	v_and_b32_e32 v81, 0xffff0000, v84
	v_lshlrev_b32_e32 v80, 16, v84
	v_and_b32_e32 v85, 0xffff0000, v93
	v_lshlrev_b32_e32 v84, 16, v93
	v_and_b32_e32 v87, 0xffff0000, v92
	v_lshlrev_b32_e32 v86, 16, v92
	v_and_b32_e32 v93, 0xffff0000, v101
	v_lshlrev_b32_e32 v92, 16, v101
	v_and_b32_e32 v95, 0xffff0000, v100
	v_lshlrev_b32_e32 v94, 16, v100
	v_and_b32_e32 v101, 0xffff0000, v71
	v_lshlrev_b32_e32 v100, 16, v71
	v_and_b32_e32 v71, 0xffff0000, v70
	v_lshlrev_b32_e32 v70, 16, v70
	v_add_f32_e32 v56, v144, v56
	v_pk_mul_f32 v[142:143], v[70:71], v[70:71]
	v_add_f32_e32 v56, v145, v56
	v_add_f32_e32 v56, v142, v56
	v_pk_mul_f32 v[140:141], v[100:101], v[100:101]
	v_add_f32_e32 v56, v143, v56
	v_and_b32_e32 v97, 0xffff0000, v99
	v_lshlrev_b32_e32 v96, 16, v99
	v_and_b32_e32 v99, 0xffff0000, v98
	v_lshlrev_b32_e32 v98, 16, v98
	v_add_f32_e32 v56, v140, v56
	v_pk_mul_f32 v[138:139], v[98:99], v[98:99]
	v_add_f32_e32 v56, v141, v56
	v_add_f32_e32 v56, v138, v56
	v_pk_mul_f32 v[136:137], v[96:97], v[96:97]
	v_add_f32_e32 v56, v139, v56
	v_add_f32_e32 v56, v136, v56
	v_pk_mul_f32 v[134:135], v[94:95], v[94:95]
	v_add_f32_e32 v56, v137, v56
	v_add_f32_e32 v56, v134, v56
	v_pk_mul_f32 v[132:133], v[92:93], v[92:93]
	v_add_f32_e32 v56, v135, v56
	v_and_b32_e32 v89, 0xffff0000, v91
	v_lshlrev_b32_e32 v88, 16, v91
	v_and_b32_e32 v91, 0xffff0000, v90
	v_lshlrev_b32_e32 v90, 16, v90
	v_add_f32_e32 v56, v132, v56
	v_pk_mul_f32 v[130:131], v[90:91], v[90:91]
	v_add_f32_e32 v56, v133, v56
	v_add_f32_e32 v56, v130, v56
	v_pk_mul_f32 v[128:129], v[88:89], v[88:89]
	v_add_f32_e32 v56, v131, v56
	v_add_f32_e32 v56, v128, v56
	v_pk_mul_f32 v[126:127], v[86:87], v[86:87]
	v_add_f32_e32 v56, v129, v56
	v_add_f32_e32 v56, v126, v56
	v_pk_mul_f32 v[124:125], v[84:85], v[84:85]
	v_add_f32_e32 v56, v127, v56
	v_add_f32_e32 v56, v124, v56
	v_pk_mul_f32 v[122:123], v[80:81], v[80:81]
	v_add_f32_e32 v56, v125, v56
	v_add_f32_e32 v56, v122, v56
	v_pk_mul_f32 v[120:121], v[78:79], v[78:79]
	v_add_f32_e32 v56, v123, v56
	v_add_f32_e32 v56, v120, v56
	v_pk_mul_f32 v[118:119], v[74:75], v[74:75]
	v_add_f32_e32 v56, v121, v56
	v_add_f32_e32 v56, v118, v56
	v_pk_mul_f32 v[116:117], v[72:73], v[72:73]
	v_add_f32_e32 v56, v119, v56
	v_add_f32_e32 v56, v116, v56
	v_add_f32_e32 v56, v117, v56
	global_load_dwordx4 v[60:63], v[82:83], off offset:320
	global_load_dwordx4 v[64:67], v[82:83], off offset:352
	global_load_dwordx4 v[138:141], v76, s[28:29] offset:400
	global_load_dwordx4 v[142:145], v76, s[28:29] offset:384
	ds_bpermute_b32 v57, v196, v56
	v_ashrrev_i32_e32 v199, 3, v106
	s_waitcnt lgkmcnt(0)
; __device__ __forceinline__ unsigned cvt_pk_bf16(float lo, float hi) { f32x2 v = {lo, hi}; bf16x2_t b = __builtin_convertvector(v, bf16x2_t); return __builtin_bit_cast(unsigned, b); }
; __device__ __forceinline__ float bf2f(unsigned short v) { return __uint_as_float(((unsigned)v) << 16); }
; template <int DQK, bool MOBA>
; __device__ __forceinline__ void attn_unit(const Args& A, int b, int h, int qb, lptr lds) {
;     ...
;         const float scn = __builtin_amdgcn_rsqf(ssn * (1.0f / 128.0f) + 1e-6f) * A.qscale;
; #pragma unroll
;         for (int s = 0; s < 8; ++s) {
;             const f32x4 g0 = *(const f32x4*)(A.gq_n + 16 * s + 8 * hi), g1 = *(const f32x4*)(A.gq_n + 16 * s + 8 * hi + 4);
;             u32x4 w;
;             w.x = cvt_pk_bf16(bf2f((unsigned short)qf[s][0]) * scn * g0[0], bf2f((unsigned short)qf[s][1]) * scn * g0[1]);
;             w.y = cvt_pk_bf16(bf2f((unsigned short)qf[s][2]) * scn * g0[2], bf2f((unsigned short)qf[s][3]) * scn * g0[3]);
;             w.z = cvt_pk_bf16(bf2f((unsigned short)qf[s][4]) * scn * g1[0], bf2f((unsigned short)qf[s][5]) * scn * g1[1]);
;             w.w = cvt_pk_bf16(bf2f((unsigned short)qf[s][6]) * scn * g1[2], bf2f((unsigned short)qf[s][7]) * scn * g1[3]);
;             qf[s] = __builtin_bit_cast(bf16x8, w);
;         }
;         if (DQK == 192) {
;             float ssr = 0.f;
; #pragma unroll
;             for (int s = 8; s < NS; ++s)
; #pragma unroll
;                 for (int e = 0; e < 8; ++e) { const float f = bf2f((unsigned short)qf[s][e]); ssr += f * f; }
;             ssr += __shfl_xor(ssr, 32);
;             const float scr = __builtin_amdgcn_rsqf(ssr * (1.0f / 64.0f) + 1e-6f);
; #pragma unroll
;             for (int sp = 0; sp < 2; ++sp) {
;                 const int i0 = 16 * sp + 8 * hi;
;                 float o1[8], o2[8];
;                 const f32x4 ga0 = *(const f32x4*)(A.gq_r + i0), ga1 = *(const f32x4*)(A.gq_r + i0 + 4), gb0 = *(const f32x4*)(A.gq_r + 32 + i0), gb1 = *(const f32x4*)(A.gq_r + 32 + i0 + 4);
;                 const f32x4 cc0 = *(const f32x4*)(A.cosT + (size_t)qrow * 32 + i0), cc1 = *(const f32x4*)(A.cosT + (size_t)qrow * 32 + i0 + 4);
;                 const f32x4 ss0 = *(const f32x4*)(A.sinT + (size_t)qrow * 32 + i0), ss1 = *(const f32x4*)(A.sinT + (size_t)qrow * 32 + i0 + 4);
	v_add_f32_e32 v56, v56, v57
	v_fmamk_f32 v56, v56, 0x3c000000, v204
	v_rsq_f32_e32 v68, v56
	global_load_dwordx4 v[56:59], v76, s[28:29] offset:464
	global_load_dwordx4 v[146:149], v76, s[28:29] offset:448
	v_mul_f32_e32 v68, 0x3dd53b94, v68
	v_pk_mul_f32 v[82:83], v[68:69], v[200:201] op_sel_hi:[0,1]
	v_pk_mul_f32 v[52:53], v[52:53], v[82:83]
	s_nop 0
	v_cvt_pk_bf16_f32 v112, v52, v53
	v_pk_mul_f32 v[52:53], v[68:69], v[194:195] op_sel_hi:[0,1]
	v_pk_mul_f32 v[52:53], v[54:55], v[52:53]
	s_nop 0
	v_cvt_pk_bf16_f32 v113, v52, v53
	v_pk_mul_f32 v[52:53], v[68:69], v[192:193] op_sel_hi:[0,1]
	v_pk_mul_f32 v[48:49], v[48:49], v[52:53]
	s_nop 0
	v_cvt_pk_bf16_f32 v114, v48, v49
	v_pk_mul_f32 v[48:49], v[68:69], v[188:189] op_sel_hi:[0,1]
	v_pk_mul_f32 v[48:49], v[50:51], v[48:49]
	v_mov_b32_e32 v189, v181
	v_cvt_pk_bf16_f32 v115, v48, v49
	v_pk_mul_f32 v[48:49], v[68:69], v[186:187] op_sel_hi:[0,1]
	v_pk_mul_f32 v[44:45], v[44:45], v[48:49]
	v_mov_b32_e32 v187, v181
	v_cvt_pk_bf16_f32 v116, v44, v45
	v_pk_mul_f32 v[44:45], v[68:69], v[176:177] op_sel_hi:[0,1]
	v_pk_mul_f32 v[44:45], v[46:47], v[44:45]
	s_nop 0
	v_cvt_pk_bf16_f32 v117, v44, v45
	v_pk_mul_f32 v[44:45], v[68:69], v[174:175] op_sel_hi:[0,1]
	v_pk_mul_f32 v[40:41], v[40:41], v[44:45]
	s_nop 0
	v_cvt_pk_bf16_f32 v118, v40, v41
	v_pk_mul_f32 v[40:41], v[68:69], v[170:171] op_sel_hi:[0,1]
	v_pk_mul_f32 v[40:41], v[42:43], v[40:41]
	s_nop 0
	v_cvt_pk_bf16_f32 v119, v40, v41
	v_pk_mul_f32 v[40:41], v[68:69], v[168:169] op_sel_hi:[0,1]
	v_pk_mul_f32 v[36:37], v[36:37], v[40:41]
	s_waitcnt vmcnt(5)
	v_and_b32_e32 v169, 0xffff0000, v61
	v_cvt_pk_bf16_f32 v120, v36, v37
	v_pk_mul_f32 v[36:37], v[68:69], v[164:165] op_sel_hi:[0,1]
	v_pk_mul_f32 v[36:37], v[38:39], v[36:37]
	v_and_b32_e32 v165, 0xffff0000, v1
	v_cvt_pk_bf16_f32 v121, v36, v37
	v_pk_mul_f32 v[36:37], v[68:69], v[162:163] op_sel_hi:[0,1]
	v_pk_mul_f32 v[32:33], v[32:33], v[36:37]
	v_lshlrev_b32_e32 v164, 16, v1
	v_cvt_pk_bf16_f32 v122, v32, v33
	v_pk_mul_f32 v[32:33], v[68:69], v[158:159] op_sel_hi:[0,1]
	v_pk_mul_f32 v[32:33], v[34:35], v[32:33]
	v_and_b32_e32 v1, 0xffff0000, v0
	v_cvt_pk_bf16_f32 v123, v32, v33
	v_pk_mul_f32 v[32:33], v[68:69], v[156:157] op_sel_hi:[0,1]
	v_pk_mul_f32 v[28:29], v[28:29], v[32:33]
	v_lshlrev_b32_e32 v0, 16, v0
	v_cvt_pk_bf16_f32 v124, v28, v29
	v_pk_mul_f32 v[28:29], v[68:69], v[154:155] op_sel_hi:[0,1]
	v_pk_mul_f32 v[28:29], v[30:31], v[28:29]
	v_pk_mul_f32 v[172:173], v[0:1], v[0:1]
	v_cvt_pk_bf16_f32 v125, v28, v29
	v_pk_mul_f32 v[28:29], v[68:69], v[152:153] op_sel_hi:[0,1]
	v_pk_mul_f32 v[24:25], v[24:25], v[28:29]
	global_load_dwordx4 v[28:31], v76, s[30:31] offset:16
	global_load_dwordx4 v[32:35], v76, s[30:31]
	global_load_dwordx4 v[36:39], v76, s[30:31] offset:144
	global_load_dwordx4 v[40:43], v76, s[30:31] offset:128
	v_cvt_pk_bf16_f32 v126, v24, v25
	v_pk_mul_f32 v[24:25], v[68:69], v[150:151] op_sel_hi:[0,1]
	v_pk_mul_f32 v[24:25], v[26:27], v[24:25]
	v_pk_mul_f32 v[166:167], v[164:165], v[164:165]
	v_cvt_pk_bf16_f32 v127, v24, v25
	v_pk_mul_f32 v[24:25], v[68:69], v[104:105] op_sel_hi:[0,1]
	v_pk_mul_f32 v[20:21], v[20:21], v[24:25]
	v_and_b32_e32 v151, 0xffff0000, v3
	v_cvt_pk_bf16_f32 v128, v20, v21
	v_pk_mul_f32 v[20:21], v[68:69], v[102:103] op_sel_hi:[0,1]
	v_pk_mul_f32 v[20:21], v[22:23], v[20:21]
	v_lshlrev_b32_e32 v150, 16, v3
	v_cvt_pk_bf16_f32 v129, v20, v21
	v_pk_mul_f32 v[20:21], v[68:69], v[70:71] op_sel_hi:[0,1]
	v_pk_mul_f32 v[16:17], v[16:17], v[20:21]
	v_and_b32_e32 v3, 0xffff0000, v2
	v_cvt_pk_bf16_f32 v130, v16, v17
	v_pk_mul_f32 v[16:17], v[68:69], v[100:101] op_sel_hi:[0,1]
	v_pk_mul_f32 v[16:17], v[18:19], v[16:17]
	v_lshlrev_b32_e32 v2, 16, v2
	v_cvt_pk_bf16_f32 v131, v16, v17
	v_pk_mul_f32 v[16:17], v[68:69], v[98:99] op_sel_hi:[0,1]
	v_pk_mul_f32 v[12:13], v[12:13], v[16:17]
	v_pk_mul_f32 v[160:161], v[2:3], v[2:3]
	v_cvt_pk_bf16_f32 v132, v12, v13
	v_pk_mul_f32 v[12:13], v[68:69], v[96:97] op_sel_hi:[0,1]
	v_pk_mul_f32 v[12:13], v[14:15], v[12:13]
	v_pk_mul_f32 v[154:155], v[150:151], v[150:151]
	v_cvt_pk_bf16_f32 v133, v12, v13
	v_pk_mul_f32 v[12:13], v[68:69], v[94:95] op_sel_hi:[0,1]
	v_pk_mul_f32 v[8:9], v[8:9], v[12:13]
	v_and_b32_e32 v105, 0xffff0000, v5
	v_cvt_pk_bf16_f32 v134, v8, v9
	v_pk_mul_f32 v[8:9], v[68:69], v[92:93] op_sel_hi:[0,1]
	v_pk_mul_f32 v[8:9], v[10:11], v[8:9]
	v_lshlrev_b32_e32 v104, 16, v5
	v_cvt_pk_bf16_f32 v135, v8, v9
	v_pk_mul_f32 v[8:9], v[68:69], v[90:91] op_sel_hi:[0,1]
	s_waitcnt vmcnt(6)
	v_pk_mul_f32 v[8:9], v[142:143], v[8:9]
	v_and_b32_e32 v5, 0xffff0000, v4
	v_cvt_pk_bf16_f32 v136, v8, v9
	v_pk_mul_f32 v[8:9], v[68:69], v[88:89] op_sel_hi:[0,1]
	v_pk_mul_f32 v[8:9], v[144:145], v[8:9]
	v_lshlrev_b32_e32 v4, 16, v4
	v_cvt_pk_bf16_f32 v137, v8, v9
	v_pk_mul_f32 v[8:9], v[68:69], v[86:87] op_sel_hi:[0,1]
	v_pk_mul_f32 v[8:9], v[138:139], v[8:9]
	v_pk_mul_f32 v[142:143], v[104:105], v[104:105]
	v_cvt_pk_bf16_f32 v138, v8, v9
	v_pk_mul_f32 v[8:9], v[68:69], v[84:85] op_sel_hi:[0,1]
	v_pk_mul_f32 v[8:9], v[140:141], v[8:9]
	v_lshlrev_b32_e32 v168, 16, v61
	v_cvt_pk_bf16_f32 v139, v8, v9
	v_pk_mul_f32 v[8:9], v[68:69], v[80:81] op_sel_hi:[0,1]
	s_waitcnt vmcnt(4)
; __device__ __forceinline__ float bf2f(unsigned short v) { return __uint_as_float(((unsigned)v) << 16); }
; template <int DQK, bool MOBA>
; __device__ __forceinline__ void attn_unit(const Args& A, int b, int h, int qb, lptr lds) {
;     ...
;             for (int sp = 0; sp < 2; ++sp) {
;                 const int i0 = 16 * sp + 8 * hi;
;                 float o1[8], o2[8];
;                 const f32x4 ga0 = *(const f32x4*)(A.gq_r + i0), ga1 = *(const f32x4*)(A.gq_r + i0 + 4), gb0 = *(const f32x4*)(A.gq_r + 32 + i0), gb1 = *(const f32x4*)(A.gq_r + 32 + i0 + 4);
;                 const f32x4 cc0 = *(const f32x4*)(A.cosT + (size_t)qrow * 32 + i0), cc1 = *(const f32x4*)(A.cosT + (size_t)qrow * 32 + i0 + 4);
;                 const f32x4 ss0 = *(const f32x4*)(A.sinT + (size_t)qrow * 32 + i0), ss1 = *(const f32x4*)(A.sinT + (size_t)qrow * 32 + i0 + 4);
; #pragma unroll
;                 for (int e = 0; e < 8; ++e) {
;                     const float x1 = bf2f((unsigned short)qf[(NS == 12 ? 8 : 0) + sp][e]) * scr * (e < 4 ? ga0[e & 3] : ga1[e & 3]);
;                     const float x2 = bf2f((unsigned short)qf[(NS == 12 ? 10 : 0) + sp][e]) * scr * (e < 4 ? gb0[e & 3] : gb1[e & 3]);
;                     const float c = e < 4 ? cc0[e & 3] : cc1[e & 3], sn = e < 4 ? ss0[e & 3] : ss1[e & 3];
;                     o1[e] = (x1 * c - x2 * sn) * A.qscale; o2[e] = (x2 * c + x1 * sn) * A.qscale;
;                 }
	v_pk_mul_f32 v[8:9], v[146:147], v[8:9]
	v_pk_mul_f32 v[146:147], v[4:5], v[4:5]
	v_cvt_pk_bf16_f32 v140, v8, v9
	v_pk_mul_f32 v[8:9], v[68:69], v[78:79] op_sel_hi:[0,1]
	v_pk_mul_f32 v[70:71], v[148:149], v[8:9]
	v_lshlrev_b64 v[8:9], 7, v[184:185]
	v_lshl_add_u64 v[10:11], s[76:77], 0, v[8:9]
	v_lshl_add_u64 v[12:13], v[10:11], 0, v[76:77]
	global_load_dwordx4 v[44:47], v[12:13], off offset:16
	global_load_dwordx4 v[48:51], v[12:13], off
	v_lshl_add_u64 v[8:9], s[78:79], 0, v[8:9]
	v_lshl_add_u64 v[24:25], v[8:9], 0, v[76:77]
	global_load_dwordx4 v[52:55], v[24:25], off offset:16
	global_load_dwordx4 v[78:81], v[24:25], off
	global_load_dwordx4 v[20:23], v76, s[30:31] offset:80
	global_load_dwordx4 v[82:85], v76, s[30:31] offset:64
	global_load_dwordx4 v[16:19], v76, s[30:31] offset:208
	global_load_dwordx4 v[86:89], v76, s[30:31] offset:192
	global_load_dwordx4 v[8:11], v[12:13], off offset:80
	global_load_dwordx4 v[90:93], v[12:13], off offset:64
	s_nop 0
	global_load_dwordx4 v[12:15], v[24:25], off offset:80
	global_load_dwordx4 v[94:97], v[24:25], off offset:64
	v_add_f32_e32 v69, v172, v173
	v_add_f32_e32 v69, v166, v69
	v_add_f32_e32 v69, v167, v69
	v_add_f32_e32 v69, v160, v69
	v_add_f32_e32 v69, v161, v69
	v_add_f32_e32 v69, v154, v69
	v_add_f32_e32 v69, v155, v69
	v_add_f32_e32 v69, v146, v69
	v_add_f32_e32 v69, v147, v69
	v_and_b32_e32 v25, 0xffff0000, v7
	v_lshlrev_b32_e32 v24, 16, v7
	v_and_b32_e32 v7, 0xffff0000, v6
	v_lshlrev_b32_e32 v6, 16, v6
	v_add_f32_e32 v69, v142, v69
	v_pk_mul_f32 v[100:101], v[6:7], v[6:7]
	v_add_f32_e32 v69, v143, v69
	v_add_f32_e32 v69, v100, v69
	v_pk_mul_f32 v[76:77], v[24:25], v[24:25]
	v_add_f32_e32 v69, v101, v69
	v_and_b32_e32 v61, 0xffff0000, v60
	v_lshlrev_b32_e32 v60, 16, v60
	v_add_f32_e32 v69, v76, v69
	v_pk_mul_f32 v[174:175], v[60:61], v[60:61]
	v_add_f32_e32 v69, v77, v69
	v_add_f32_e32 v69, v174, v69
	v_pk_mul_f32 v[170:171], v[168:169], v[168:169]
	v_add_f32_e32 v69, v175, v69
	v_and_b32_e32 v157, 0xffff0000, v63
	v_lshlrev_b32_e32 v156, 16, v63
	v_and_b32_e32 v63, 0xffff0000, v62
	v_lshlrev_b32_e32 v62, 16, v62
	v_add_f32_e32 v69, v170, v69
	v_pk_mul_f32 v[162:163], v[62:63], v[62:63]
	v_add_f32_e32 v69, v171, v69
	v_add_f32_e32 v69, v162, v69
	v_pk_mul_f32 v[158:159], v[156:157], v[156:157]
	v_add_f32_e32 v69, v163, v69
	v_and_b32_e32 v153, 0xffff0000, v65
	v_lshlrev_b32_e32 v152, 16, v65
	v_and_b32_e32 v65, 0xffff0000, v64
	v_lshlrev_b32_e32 v64, 16, v64
	v_add_f32_e32 v69, v158, v69
	v_pk_mul_f32 v[148:149], v[64:65], v[64:65]
	v_add_f32_e32 v69, v159, v69
	v_add_f32_e32 v69, v148, v69
	v_pk_mul_f32 v[144:145], v[152:153], v[152:153]
	v_add_f32_e32 v69, v149, v69
	v_and_b32_e32 v27, 0xffff0000, v67
	v_lshlrev_b32_e32 v26, 16, v67
	v_and_b32_e32 v67, 0xffff0000, v66
	v_lshlrev_b32_e32 v66, 16, v66
	v_add_f32_e32 v69, v144, v69
	v_pk_mul_f32 v[102:103], v[66:67], v[66:67]
	v_add_f32_e32 v69, v145, v69
	v_add_f32_e32 v69, v102, v69
	v_pk_mul_f32 v[98:99], v[26:27], v[26:27]
	v_add_f32_e32 v69, v103, v69
	v_add_f32_e32 v69, v98, v69
	v_add_f32_e32 v69, v99, v69
	ds_bpermute_b32 v76, v196, v69
	v_cvt_pk_bf16_f32 v141, v70, v71
	v_pk_mul_f32 v[70:71], v[68:69], v[74:75] op_sel_hi:[0,1]
	v_pk_mul_f32 v[56:57], v[56:57], v[70:71]
	s_nop 0
	v_cvt_pk_bf16_f32 v142, v56, v57
	s_waitcnt lgkmcnt(0)
	v_add_f32_e32 v56, v69, v76
	v_fmamk_f32 v56, v56, 0x3c800000, v204
	v_rsq_f32_e32 v56, v56
	v_pk_mul_f32 v[68:69], v[68:69], v[72:73] op_sel_hi:[0,1]
	v_pk_mul_f32 v[58:59], v[58:59], v[68:69]
	v_pk_mul_f32 v[0:1], v[56:57], v[0:1] op_sel_hi:[0,1]
	s_waitcnt vmcnt(14)
	v_pk_mul_f32 v[0:1], v[32:33], v[0:1]
	v_pk_mul_f32 v[32:33], v[56:57], v[60:61] op_sel_hi:[0,1]
	s_waitcnt vmcnt(12)
	v_pk_mul_f32 v[32:33], v[40:41], v[32:33]
	v_pk_mul_f32 v[2:3], v[56:57], v[2:3] op_sel_hi:[0,1]
	s_waitcnt vmcnt(8)
	v_pk_mul_f32 v[40:41], v[78:79], v[32:33]
	v_pk_mul_f32 v[2:3], v[28:29], v[2:3]
	v_pk_fma_f32 v[40:41], v[48:49], v[0:1], v[40:41] neg_lo:[0,0,1] neg_hi:[0,0,1]
	v_pk_mul_f32 v[0:1], v[78:79], v[0:1]
	v_pk_mul_f32 v[28:29], v[56:57], v[62:63] op_sel_hi:[0,1]
	v_pk_fma_f32 v[0:1], v[48:49], v[32:33], v[0:1]
	v_pk_mul_f32 v[32:33], v[56:57], v[164:165] op_sel_hi:[0,1]
	v_pk_mul_f32 v[32:33], v[34:35], v[32:33]
	v_pk_mul_f32 v[34:35], v[56:57], v[168:169] op_sel_hi:[0,1]
	v_pk_mul_f32 v[34:35], v[42:43], v[34:35]
	v_pk_mul_f32 v[28:29], v[36:37], v[28:29]
	v_pk_mul_f32 v[42:43], v[80:81], v[34:35]
	v_pk_mul_f32 v[0:1], v[0:1], s[94:95] op_sel_hi:[1,0]
	v_pk_fma_f32 v[42:43], v[50:51], v[32:33], v[42:43] neg_lo:[0,0,1] neg_hi:[0,0,1]
	v_pk_mul_f32 v[32:33], v[80:81], v[32:33]
	v_cvt_pk_bf16_f32 v144, v0, v1
	v_pk_fma_f32 v[32:33], v[50:51], v[34:35], v[32:33]
	v_pk_mul_f32 v[34:35], v[52:53], v[28:29]
	v_pk_mul_f32 v[0:1], v[56:57], v[4:5] op_sel_hi:[0,1]
	v_pk_fma_f32 v[34:35], v[44:45], v[2:3], v[34:35] neg_lo:[0,0,1] neg_hi:[0,0,1]
	v_pk_mul_f32 v[2:3], v[52:53], v[2:3]
	s_waitcnt vmcnt(6)
	v_pk_mul_f32 v[0:1], v[82:83], v[0:1]
	v_pk_fma_f32 v[2:3], v[44:45], v[28:29], v[2:3]
	v_pk_mul_f32 v[28:29], v[56:57], v[150:151] op_sel_hi:[0,1]
	v_pk_mul_f32 v[2:3], v[2:3], s[94:95] op_sel_hi:[1,0]
	v_pk_mul_f32 v[28:29], v[30:31], v[28:29]
	v_pk_mul_f32 v[30:31], v[56:57], v[156:157] op_sel_hi:[0,1]
	v_cvt_pk_bf16_f32 v146, v2, v3
	v_pk_mul_f32 v[2:3], v[56:57], v[64:65] op_sel_hi:[0,1]
	v_pk_mul_f32 v[30:31], v[38:39], v[30:31]
	s_waitcnt vmcnt(4)
	v_pk_mul_f32 v[2:3], v[86:87], v[2:3]
	v_pk_mul_f32 v[36:37], v[54:55], v[30:31]
	s_waitcnt vmcnt(0)
; __device__ __forceinline__ unsigned cvt_pk_bf16(float lo, float hi) { f32x2 v = {lo, hi}; bf16x2_t b = __builtin_convertvector(v, bf16x2_t); return __builtin_bit_cast(unsigned, b); }
; __device__ __forceinline__ float bf2f(unsigned short v) { return __uint_as_float(((unsigned)v) << 16); }
; template <int DQK, bool MOBA>
; __device__ __forceinline__ void attn_unit(const Args& A, int b, int h, int qb, lptr lds) {
;     ...
; #pragma unroll
;                 for (int e = 0; e < 8; ++e) {
;                     const float x1 = bf2f((unsigned short)qf[(NS == 12 ? 8 : 0) + sp][e]) * scr * (e < 4 ? ga0[e & 3] : ga1[e & 3]);
;                     const float x2 = bf2f((unsigned short)qf[(NS == 12 ? 10 : 0) + sp][e]) * scr * (e < 4 ? gb0[e & 3] : gb1[e & 3]);
;                     const float c = e < 4 ? cc0[e & 3] : cc1[e & 3], sn = e < 4 ? ss0[e & 3] : ss1[e & 3];
;                     o1[e] = (x1 * c - x2 * sn) * A.qscale; o2[e] = (x2 * c + x1 * sn) * A.qscale;
;                 }
;                 u32x4 w1, w2;
;                 w1.x = cvt_pk_bf16(o1[0], o1[1]); w1.y = cvt_pk_bf16(o1[2], o1[3]); w1.z = cvt_pk_bf16(o1[4], o1[5]); w1.w = cvt_pk_bf16(o1[6], o1[7]);
;                 w2.x = cvt_pk_bf16(o2[0], o2[1]); w2.y = cvt_pk_bf16(o2[2], o2[3]); w2.z = cvt_pk_bf16(o2[4], o2[5]); w2.w = cvt_pk_bf16(o2[6], o2[7]);
;                 qf[(NS == 12 ? 8 : 0) + sp] = __builtin_bit_cast(bf16x8, w1); qf[(NS == 12 ? 10 : 0) + sp] = __builtin_bit_cast(bf16x8, w2);
;     ...
;         float qss = 0.f;
; #pragma unroll
;         for (int s = 0; s < NS; ++s)
; #pragma unroll
;             for (int e = 0; e < 8; ++e) { const float f = bf2f((unsigned short)qf[s][e]); qss += f * f; }
;         qss += __shfl_xor(qss, 32);
;         float gmx = fmaxf(fabsf(A.gk_n[lane]), fabsf(A.gk_n[lane + 64]));
	v_pk_mul_f32 v[4:5], v[94:95], v[2:3]
	v_pk_fma_f32 v[36:37], v[46:47], v[28:29], v[36:37] neg_lo:[0,0,1] neg_hi:[0,0,1]
	v_pk_mul_f32 v[28:29], v[54:55], v[28:29]
	v_pk_fma_f32 v[4:5], v[90:91], v[0:1], v[4:5] neg_lo:[0,0,1] neg_hi:[0,0,1]
	v_pk_mul_f32 v[0:1], v[94:95], v[0:1]
	v_pk_fma_f32 v[28:29], v[46:47], v[30:31], v[28:29]
	v_pk_fma_f32 v[0:1], v[90:91], v[2:3], v[0:1]
	v_pk_mul_f32 v[28:29], v[28:29], s[94:95] op_sel_hi:[1,0]
	v_pk_mul_f32 v[0:1], v[0:1], s[94:95] op_sel_hi:[1,0]
	v_cvt_pk_bf16_f32 v147, v28, v29
	v_pk_mul_f32 v[28:29], v[56:57], v[152:153] op_sel_hi:[0,1]
	v_cvt_pk_bf16_f32 v152, v0, v1
	v_and_b32_e32 v0, 0xffff0000, v112
	v_lshlrev_b32_e32 v1, 16, v112
	v_mul_f32_e32 v0, v0, v0
	v_fmac_f32_e32 v0, v1, v1
	v_lshlrev_b32_e32 v1, 16, v113
	v_fmac_f32_e32 v0, v1, v1
	v_and_b32_e32 v1, 0xffff0000, v113
	v_fmac_f32_e32 v0, v1, v1
	v_lshlrev_b32_e32 v1, 16, v114
	v_fmac_f32_e32 v0, v1, v1
	v_and_b32_e32 v1, 0xffff0000, v114
	v_fmac_f32_e32 v0, v1, v1
	v_lshlrev_b32_e32 v1, 16, v115
	v_fmac_f32_e32 v0, v1, v1
	v_and_b32_e32 v1, 0xffff0000, v115
	v_fmac_f32_e32 v0, v1, v1
	v_lshlrev_b32_e32 v1, 16, v116
	v_fmac_f32_e32 v0, v1, v1
	v_and_b32_e32 v1, 0xffff0000, v116
	v_fmac_f32_e32 v0, v1, v1
	v_lshlrev_b32_e32 v1, 16, v117
	v_fmac_f32_e32 v0, v1, v1
	v_and_b32_e32 v1, 0xffff0000, v117
	v_fmac_f32_e32 v0, v1, v1
	v_lshlrev_b32_e32 v1, 16, v118
	v_fmac_f32_e32 v0, v1, v1
	v_and_b32_e32 v1, 0xffff0000, v118
	v_fmac_f32_e32 v0, v1, v1
	v_lshlrev_b32_e32 v1, 16, v119
	v_fmac_f32_e32 v0, v1, v1
	v_and_b32_e32 v1, 0xffff0000, v119
	v_fmac_f32_e32 v0, v1, v1
	v_lshlrev_b32_e32 v1, 16, v120
	v_fmac_f32_e32 v0, v1, v1
	v_and_b32_e32 v1, 0xffff0000, v120
	v_fmac_f32_e32 v0, v1, v1
	v_lshlrev_b32_e32 v1, 16, v121
	v_fmac_f32_e32 v0, v1, v1
	v_and_b32_e32 v1, 0xffff0000, v121
	v_fmac_f32_e32 v0, v1, v1
	v_lshlrev_b32_e32 v1, 16, v122
	v_fmac_f32_e32 v0, v1, v1
	v_and_b32_e32 v1, 0xffff0000, v122
	v_fmac_f32_e32 v0, v1, v1
	v_lshlrev_b32_e32 v1, 16, v123
	v_fmac_f32_e32 v0, v1, v1
	v_and_b32_e32 v1, 0xffff0000, v123
	v_fmac_f32_e32 v0, v1, v1
	v_lshlrev_b32_e32 v1, 16, v124
	v_fmac_f32_e32 v0, v1, v1
	v_and_b32_e32 v1, 0xffff0000, v124
	v_fmac_f32_e32 v0, v1, v1
	v_lshlrev_b32_e32 v1, 16, v125
	v_fmac_f32_e32 v0, v1, v1
	v_and_b32_e32 v1, 0xffff0000, v125
	v_fmac_f32_e32 v0, v1, v1
	v_lshlrev_b32_e32 v1, 16, v126
	v_fmac_f32_e32 v0, v1, v1
	v_and_b32_e32 v1, 0xffff0000, v126
	v_fmac_f32_e32 v0, v1, v1
	v_lshlrev_b32_e32 v1, 16, v127
	v_fmac_f32_e32 v0, v1, v1
	v_and_b32_e32 v1, 0xffff0000, v127
	v_fmac_f32_e32 v0, v1, v1
	v_lshlrev_b32_e32 v1, 16, v128
	v_fmac_f32_e32 v0, v1, v1
	v_and_b32_e32 v1, 0xffff0000, v128
	v_fmac_f32_e32 v0, v1, v1
	v_lshlrev_b32_e32 v1, 16, v129
	v_fmac_f32_e32 v0, v1, v1
	v_and_b32_e32 v1, 0xffff0000, v129
	v_fmac_f32_e32 v0, v1, v1
	v_lshlrev_b32_e32 v1, 16, v130
	v_fmac_f32_e32 v0, v1, v1
	v_and_b32_e32 v1, 0xffff0000, v130
	v_fmac_f32_e32 v0, v1, v1
	v_lshlrev_b32_e32 v1, 16, v131
	v_fmac_f32_e32 v0, v1, v1
	v_and_b32_e32 v1, 0xffff0000, v131
	v_fmac_f32_e32 v0, v1, v1
	v_lshlrev_b32_e32 v1, 16, v132
	v_fmac_f32_e32 v0, v1, v1
	v_and_b32_e32 v1, 0xffff0000, v132
	v_fmac_f32_e32 v0, v1, v1
	v_lshlrev_b32_e32 v1, 16, v133
	v_fmac_f32_e32 v0, v1, v1
	v_and_b32_e32 v1, 0xffff0000, v133
	v_fmac_f32_e32 v0, v1, v1
	v_lshlrev_b32_e32 v1, 16, v134
	v_fmac_f32_e32 v0, v1, v1
	v_and_b32_e32 v1, 0xffff0000, v134
	v_fmac_f32_e32 v0, v1, v1
	v_lshlrev_b32_e32 v1, 16, v135
	v_fmac_f32_e32 v0, v1, v1
	v_and_b32_e32 v1, 0xffff0000, v135
	v_fmac_f32_e32 v0, v1, v1
	v_lshlrev_b32_e32 v1, 16, v136
	v_fmac_f32_e32 v0, v1, v1
	v_and_b32_e32 v1, 0xffff0000, v136
	v_fmac_f32_e32 v0, v1, v1
	v_lshlrev_b32_e32 v1, 16, v137
	v_fmac_f32_e32 v0, v1, v1
	v_and_b32_e32 v1, 0xffff0000, v137
	v_pk_mul_f32 v[6:7], v[56:57], v[6:7] op_sel_hi:[0,1]
	v_fmac_f32_e32 v0, v1, v1
	v_lshlrev_b32_e32 v1, 16, v138
	v_pk_mul_f32 v[4:5], v[4:5], s[94:95] op_sel_hi:[1,0]
	v_pk_mul_f32 v[6:7], v[20:21], v[6:7]
	v_pk_mul_f32 v[20:21], v[56:57], v[66:67] op_sel_hi:[0,1]
	v_fmac_f32_e32 v0, v1, v1
	v_lshlrev_b32_e32 v1, 2, v110
	v_pk_mul_f32 v[16:17], v[16:17], v[20:21]
	v_cvt_pk_bf16_f32 v156, v4, v5
	global_load_dword v4, v1, s[38:39]
	global_load_dword v5, v1, s[38:39] offset:256
	v_pk_mul_f32 v[20:21], v[12:13], v[16:17]
	v_pk_mul_f32 v[2:3], v[56:57], v[104:105] op_sel_hi:[0,1]
	v_pk_fma_f32 v[20:21], v[8:9], v[6:7], v[20:21] neg_lo:[0,0,1] neg_hi:[0,0,1]
	v_pk_mul_f32 v[6:7], v[12:13], v[6:7]
	v_pk_mul_f32 v[28:29], v[88:89], v[28:29]
	v_pk_fma_f32 v[6:7], v[8:9], v[16:17], v[6:7]
	v_pk_mul_f32 v[2:3], v[84:85], v[2:3]
	v_pk_mul_f32 v[6:7], v[6:7], s[94:95] op_sel_hi:[1,0]
	v_pk_mul_f32 v[30:31], v[96:97], v[28:29]
	v_cvt_pk_bf16_f32 v154, v6, v7
	global_load_dword v6, v1, s[40:41]
	v_pk_fma_f32 v[30:31], v[92:93], v[2:3], v[30:31] neg_lo:[0,0,1] neg_hi:[0,0,1]
	v_pk_mul_f32 v[2:3], v[96:97], v[2:3]
	v_and_b32_e32 v1, 0xffff0000, v140
	v_pk_fma_f32 v[2:3], v[92:93], v[28:29], v[2:3]
	v_cvt_pk_bf16_f32 v143, v58, v59
	v_pk_mul_f32 v[2:3], v[2:3], s[94:95] op_sel_hi:[1,0]
	v_pk_mul_f32 v[40:41], v[40:41], s[94:95] op_sel_hi:[1,0]
	v_cvt_pk_bf16_f32 v153, v2, v3
	v_and_b32_e32 v2, 0xffff0000, v138
	v_fmac_f32_e32 v0, v2, v2
	v_lshlrev_b32_e32 v2, 16, v139
	v_fmac_f32_e32 v0, v2, v2
	v_and_b32_e32 v2, 0xffff0000, v139
	v_fmac_f32_e32 v0, v2, v2
	v_lshlrev_b32_e32 v2, 16, v140
	v_fmac_f32_e32 v0, v2, v2
	v_fmac_f32_e32 v0, v1, v1
	v_lshlrev_b32_e32 v1, 16, v141
	v_fmac_f32_e32 v0, v1, v1
	v_and_b32_e32 v1, 0xffff0000, v141
	v_fmac_f32_e32 v0, v1, v1
	v_lshlrev_b32_e32 v1, 16, v142
	v_fmac_f32_e32 v0, v1, v1
	v_and_b32_e32 v1, 0xffff0000, v142
; __device__ __forceinline__ float bf2f(unsigned short v) { return __uint_as_float(((unsigned)v) << 16); }
; template <int DQK, bool MOBA>
; __device__ __forceinline__ void attn_unit(const Args& A, int b, int h, int qb, lptr lds) {
;     ...
;         float qss = 0.f;
; #pragma unroll
;         for (int s = 0; s < NS; ++s)
; #pragma unroll
;             for (int e = 0; e < 8; ++e) { const float f = bf2f((unsigned short)qf[s][e]); qss += f * f; }
;         qss += __shfl_xor(qss, 32);
;         float gmx = fmaxf(fabsf(A.gk_n[lane]), fabsf(A.gk_n[lane + 64]));
;         float grx = (DQK == 192) ? fabsf(A.gk_r[lane]) : 0.f;
;         float bmx = (MOBA && lane < 32) ? fabsf(A.relb[lane * 8 + h]) * 1.4426950408889634f : 0.f;
; #pragma unroll
;         for (int o_ = 1; o_ < 64; o_ <<= 1) { gmx = fmaxf(gmx, __shfl_xor(gmx, o_)); grx = fmaxf(grx, __shfl_xor(grx, o_)); bmx = fmaxf(bmx, __shfl_xor(bmx, o_)); }
;         negm = -(sqrtf(qss * (128.0f * gmx * gmx + 64.0f * grx * grx)) * 1.01f + bmx + 0.01f);
	v_fmac_f32_e32 v0, v1, v1
	v_lshlrev_b32_e32 v1, 16, v143
	v_cvt_pk_bf16_f32 v148, v40, v41
	v_fmac_f32_e32 v0, v1, v1
	v_and_b32_e32 v1, 0xffff0000, v143
	v_pk_mul_f32 v[42:43], v[42:43], s[94:95] op_sel_hi:[1,0]
	v_fmac_f32_e32 v0, v1, v1
	v_lshlrev_b32_e32 v1, 16, v148
	v_cvt_pk_bf16_f32 v149, v42, v43
	v_fmac_f32_e32 v0, v1, v1
	v_and_b32_e32 v1, 0xffff0000, v148
	v_pk_mul_f32 v[34:35], v[34:35], s[94:95] op_sel_hi:[1,0]
	v_fmac_f32_e32 v0, v1, v1
	v_lshlrev_b32_e32 v1, 16, v149
	v_cvt_pk_bf16_f32 v150, v34, v35
	v_fmac_f32_e32 v0, v1, v1
	v_and_b32_e32 v1, 0xffff0000, v149
	v_pk_mul_f32 v[36:37], v[36:37], s[94:95] op_sel_hi:[1,0]
	v_fmac_f32_e32 v0, v1, v1
	v_lshlrev_b32_e32 v1, 16, v150
	v_cvt_pk_bf16_f32 v151, v36, v37
	v_fmac_f32_e32 v0, v1, v1
	v_and_b32_e32 v1, 0xffff0000, v150
	v_fmac_f32_e32 v0, v1, v1
	v_lshlrev_b32_e32 v1, 16, v151
	v_fmac_f32_e32 v0, v1, v1
	v_and_b32_e32 v1, 0xffff0000, v151
	v_pk_mul_f32 v[30:31], v[30:31], s[94:95] op_sel_hi:[1,0]
	v_pk_mul_f32 v[12:13], v[56:57], v[26:27] op_sel_hi:[0,1]
	v_fmac_f32_e32 v0, v1, v1
	v_lshlrev_b32_e32 v1, 16, v156
	v_pk_mul_f32 v[8:9], v[56:57], v[24:25] op_sel_hi:[0,1]
	v_pk_mul_f32 v[12:13], v[18:19], v[12:13]
	v_cvt_pk_bf16_f32 v157, v30, v31
	v_fmac_f32_e32 v0, v1, v1
	v_and_b32_e32 v1, 0xffff0000, v156
	v_pk_mul_f32 v[20:21], v[20:21], s[94:95] op_sel_hi:[1,0]
	v_pk_mul_f32 v[8:9], v[22:23], v[8:9]
	v_pk_mul_f32 v[16:17], v[14:15], v[12:13]
	v_fmac_f32_e32 v0, v1, v1
	v_lshlrev_b32_e32 v1, 16, v157
	v_pk_fma_f32 v[16:17], v[10:11], v[8:9], v[16:17] neg_lo:[0,0,1] neg_hi:[0,0,1]
	v_cvt_pk_bf16_f32 v158, v20, v21
	v_fmac_f32_e32 v0, v1, v1
	v_and_b32_e32 v1, 0xffff0000, v157
	v_pk_mul_f32 v[16:17], v[16:17], s[94:95] op_sel_hi:[1,0]
	v_fmac_f32_e32 v0, v1, v1
	v_lshlrev_b32_e32 v1, 16, v158
	v_cvt_pk_bf16_f32 v159, v16, v17
	v_fmac_f32_e32 v0, v1, v1
	v_and_b32_e32 v1, 0xffff0000, v158
	v_fmac_f32_e32 v0, v1, v1
	v_lshlrev_b32_e32 v1, 16, v159
	v_pk_mul_f32 v[32:33], v[32:33], s[94:95] op_sel_hi:[1,0]
	v_fmac_f32_e32 v0, v1, v1
	v_and_b32_e32 v1, 0xffff0000, v159
	v_cvt_pk_bf16_f32 v145, v32, v33
	v_fmac_f32_e32 v0, v1, v1
	v_lshlrev_b32_e32 v1, 16, v144
	v_fmac_f32_e32 v0, v1, v1
	v_and_b32_e32 v1, 0xffff0000, v144
	v_and_b32_e32 v3, 0xffff0000, v145
	v_lshlrev_b32_e32 v2, 16, v145
	v_fmac_f32_e32 v0, v1, v1
	v_pk_mul_f32 v[2:3], v[2:3], v[2:3]
	v_and_b32_e32 v1, 0xffff0000, v146
	v_add_f32_e32 v0, v2, v0
	v_add_f32_e32 v2, v3, v0
	v_lshlrev_b32_e32 v0, 16, v146
	v_pk_mul_f32 v[0:1], v[0:1], v[0:1]
	v_pk_mul_f32 v[8:9], v[14:15], v[8:9]
	v_add_f32_e32 v0, v0, v2
	v_add_f32_e32 v2, v1, v0
	v_lshlrev_b32_e32 v1, 16, v147
	v_and_b32_e32 v0, 0xffff0000, v147
	v_pk_mul_f32 v[0:1], v[0:1], v[0:1]
	v_pk_fma_f32 v[8:9], v[10:11], v[12:13], v[8:9]
	v_add_f32_e32 v1, v1, v2
	v_add_f32_e32 v2, v0, v1
	v_and_b32_e32 v1, 0xffff0000, v152
	v_lshlrev_b32_e32 v0, 16, v152
	v_pk_mul_f32 v[0:1], v[0:1], v[0:1]
	v_pk_mul_f32 v[8:9], v[8:9], s[94:95] op_sel_hi:[1,0]
	v_add_f32_e32 v0, v0, v2
	v_add_f32_e32 v2, v1, v0
	s_waitcnt vmcnt(1)
	v_max_f32_e64 v0, |v5|, |v5|
	v_max_f32_e64 v1, |v4|, |v4|
	v_max_f32_e32 v3, v1, v0
	v_xor_b32_e32 v0, 1, v206
	v_cmp_lt_i32_e32 vcc, v0, v109
	s_waitcnt vmcnt(0)
	v_and_b32_e32 v1, 0x7fffffff, v6
	v_cvt_pk_bf16_f32 v155, v8, v9
	v_cndmask_b32_e32 v0, v206, v0, vcc
	v_lshlrev_b32_e32 v0, 2, v0
	ds_bpermute_b32 v4, v0, v3
	ds_bpermute_b32 v5, v0, v1
	v_and_b32_e32 v1, 0xffff0000, v153
	v_lshlrev_b32_e32 v0, 16, v153
	v_pk_mul_f32 v[0:1], v[0:1], v[0:1]
	s_waitcnt lgkmcnt(1)
	v_max_f32_e32 v4, v4, v4
	v_max_f32_e32 v3, v3, v4
	s_waitcnt lgkmcnt(0)
	v_max_f32_e32 v4, v5, v5
	v_max_f32_e64 v5, |v6|, |v6|
	v_xor_b32_e32 v6, 2, v206
	v_cmp_lt_i32_e32 vcc, v6, v109
	v_max_f32_e32 v4, v5, v4
	v_add_f32_e32 v0, v0, v2
	v_cndmask_b32_e32 v6, v206, v6, vcc
	v_lshlrev_b32_e32 v6, 2, v6
	ds_bpermute_b32 v7, v6, v3
	ds_bpermute_b32 v5, v6, v4
	v_and_b32_e32 v32, 15, v106
	v_lshlrev_b32_e32 v186, 4, v32
	v_add_u32_e32 v14, s4, v199
	s_waitcnt lgkmcnt(1)
	v_max_f32_e32 v2, v7, v7
	v_max_f32_e32 v2, v3, v2
	s_waitcnt lgkmcnt(0)
	v_max_f32_e32 v3, v5, v5
	v_xor_b32_e32 v5, 4, v206
	v_cmp_lt_i32_e32 vcc, v5, v109
	v_max_f32_e32 v3, v4, v3
	v_ashrrev_i32_e32 v15, 31, v14
	v_cndmask_b32_e32 v5, v206, v5, vcc
	v_lshlrev_b32_e32 v5, 2, v5
	ds_bpermute_b32 v6, v5, v2
	ds_bpermute_b32 v4, v5, v3
	v_add_f32_e32 v5, v1, v0
	v_and_b32_e32 v1, 0xffff0000, v154
	v_lshlrev_b64 v[14:15], 7, v[14:15]
	s_waitcnt lgkmcnt(1)
	v_max_f32_e32 v0, v6, v6
	v_max_f32_e32 v2, v2, v0
	s_waitcnt lgkmcnt(0)
	v_max_f32_e32 v0, v4, v4
	v_xor_b32_e32 v4, 8, v206
	v_cmp_lt_i32_e32 vcc, v4, v109
	v_max_f32_e32 v3, v3, v0
	v_lshlrev_b32_e32 v0, 16, v154
	v_cndmask_b32_e32 v4, v206, v4, vcc
	v_lshlrev_b32_e32 v4, 2, v4
	ds_bpermute_b32 v6, v4, v2
	ds_bpermute_b32 v4, v4, v3
	v_pk_mul_f32 v[0:1], v[0:1], v[0:1]
	v_lshlrev_b32_e32 v16, 4, v106
	v_add_f32_e32 v0, v0, v5
	s_waitcnt lgkmcnt(1)
	v_max_f32_e32 v6, v6, v6
	v_max_f32_e32 v2, v2, v6
	v_xor_b32_e32 v6, 16, v206
	v_cmp_lt_i32_e32 vcc, v6, v109
	s_waitcnt lgkmcnt(0)
	v_max_f32_e32 v4, v4, v4
	v_max_f32_e32 v3, v3, v4
	v_cndmask_b32_e32 v6, v206, v6, vcc
	v_lshlrev_b32_e32 v6, 2, v6
	ds_bpermute_b32 v7, v6, v2
	ds_bpermute_b32 v4, v6, v3
	v_add_f32_e32 v1, v1, v0
	v_and_b32_e32 v5, 0xffff0000, v155
	v_lshl_add_u64 v[14:15], s[86:87], 0, v[14:15]
	s_waitcnt lgkmcnt(1)
	v_max_f32_e32 v0, v7, v7
	v_max_f32_e32 v0, v2, v0
	s_waitcnt lgkmcnt(0)
	v_max_f32_e32 v2, v4, v4
	ds_bpermute_b32 v4, v196, v0
	v_max_f32_e32 v6, v3, v2
	ds_bpermute_b32 v7, v196, v6
	v_lshlrev_b32_e32 v3, 16, v155
	v_mov_b32_e32 v183, v3
	s_waitcnt lgkmcnt(1)
; template <int DQK, bool MOBA>
; __device__ __forceinline__ void attn_unit(const Args& A, int b, int h, int qb, lptr lds) {
;     ...
;         negm = -(sqrtf(qss * (128.0f * gmx * gmx + 64.0f * grx * grx)) * 1.01f + bmx + 0.01f);
;     }
;     const int NT = 4 * (own + 1);
;     u32x4 kr0, kr1, kr2, vr0, vr1; int pkr = 0;
;     kr2 = (u32x4){0u, 0u, 0u, 0u};
;     ...
;     f32x16 o[4];
; #pragma unroll
;     for (int d = 0; d < 4; ++d)
; #pragma unroll
;         for (int r = 0; r < 16; ++r) o[d][r] = 0.f;
;     float lrow = 0.f;
;     ATT_LOAD(0); ATT_WRITE(0);
;     if (NT > 1) ATT_LOAD(1);
;     __syncthreads();
	v_max_f32_e32 v2, v4, v4
	v_max_f32_e32 v2, v0, v2
	s_waitcnt lgkmcnt(0)
	v_max_f32_e32 v0, v7, v7
	v_max_f32_e32 v4, v6, v0
	v_pk_mul_f32 v[8:9], v[2:3], v[182:183]
	v_mov_b32_e32 v0, v2
	v_pk_mul_f32 v[8:9], v[2:3], v[8:9]
	v_pk_fma_f32 v[0:1], v[2:3], v[182:183], v[0:1]
	v_mul_f32_e32 v6, 0x42800000, v4
	v_mov_b32_e32 v9, v1
	v_mov_b32_e32 v7, v5
	v_pk_fma_f32 v[26:27], v[4:5], v[6:7], v[8:9]
	ds_bpermute_b32 v30, v196, v27
	v_ashrrev_i32_e32 v0, 4, v106
	v_ashrrev_i32_e32 v1, 31, v0
	v_lshlrev_b64 v[2:3], 11, v[0:1]
	v_lshl_add_u64 v[4:5], s[0:1], 0, v[2:3]
	s_waitcnt lgkmcnt(0)
	v_add_f32_e32 v27, v27, v30
	v_mul_f32_e32 v26, v26, v27
	v_mul_f32_e32 v27, 0x4f800000, v26
	v_cmp_gt_f32_e32 vcc, s35, v26
	v_lshl_add_u64 v[6:7], v[4:5], 0, v[186:187]
	v_add_u32_e32 v4, 32, v0
	v_cndmask_b32_e32 v26, v26, v27, vcc
	v_ashrrev_i32_e32 v5, 31, v4
	v_sqrt_f32_e32 v27, v26
	v_lshlrev_b64 v[28:29], 11, v[4:5]
	v_lshl_add_u64 v[8:9], s[0:1], 0, v[28:29]
	s_add_u32 s0, s92, s44
	s_addc_u32 s1, s93, s45
	s_add_u32 s0, s0, s6
	v_add_u32_e32 v30, -1, v27
	s_addc_u32 s1, s1, s7
	v_fma_f32 v31, -v30, v27, v26
	v_lshl_add_u64 v[18:19], s[0:1], 0, v[2:3]
	v_lshl_add_u64 v[22:23], s[0:1], 0, v[28:29]
	v_cmp_ge_f32_e64 s[0:1], 0, v31
	v_add_u32_e32 v31, 1, v27
	v_and_b32_e32 v188, 0x70, v16
	v_cndmask_b32_e64 v30, v27, v30, s[0:1]
	v_fma_f32 v27, -v31, v27, v26
	v_cmp_lt_f32_e64 s[0:1], 0, v27
	v_lshl_add_u64 v[10:11], v[8:9], 0, v[186:187]
	v_lshl_add_u64 v[14:15], v[14:15], 0, v[188:189]
	v_cndmask_b32_e64 v27, v30, v31, s[0:1]
	v_mul_f32_e32 v30, 0x37800000, v27
	v_cndmask_b32_e32 v27, v27, v30, vcc
	v_cmp_class_f32_e32 vcc, v26, v205
	s_mov_b32 s0, 0x3f8147ae
	s_nop 0
	s_nop 0
	s_nop 0
	v_cndmask_b32_e32 v26, v27, v26, vcc
	v_fma_f32 v26, v26, s0, 0
	v_add_f32_e32 v33, 0x3c23d70a, v26
	v_mov_b32_e32 v26, s15
	s_movk_i32 s0, 0xffe0
	v_bfi_b32 v197, s0, v26, v106
	s_or_b32 s0, s4, 64
	s_ashr_i32 s1, s0, 31
	s_lshl_b64 s[44:45], s[0:1], 11
	s_add_u32 s1, s92, s44
	s_addc_u32 s4, s93, s45
	s_add_u32 s46, s1, s6
	s_nop 0
	v_lshl_add_u64 v[22:23], v[22:23], 0, v[186:187]
	s_addc_u32 s47, s4, s7
	s_nop 0
	v_lshl_add_u64 v[26:27], s[46:47], 0, v[28:29]
	v_add_u32_e32 v30, s0, v199
	s_add_u32 s0, s90, s44
	v_lshl_add_u64 v[18:19], v[18:19], 0, v[186:187]
	v_lshl_add_u64 v[26:27], v[26:27], 0, v[186:187]
	v_ashrrev_i32_e32 v31, 31, v30
	s_addc_u32 s1, s91, s45
	s_nop 0
	v_lshlrev_b64 v[30:31], 7, v[30:31]
	global_load_dwordx4 v[160:163], v[26:27], off
	v_lshl_add_u64 v[26:27], s[46:47], 0, v[2:3]
	s_add_u32 s0, s0, s6
	v_lshl_add_u64 v[26:27], v[26:27], 0, v[186:187]
	v_lshl_add_u64 v[30:31], s[86:87], 0, v[30:31]
	s_addc_u32 s1, s1, s7
	v_lshl_add_u64 v[30:31], v[30:31], 0, v[188:189]
	global_load_dwordx4 v[164:167], v[26:27], off
	global_load_dwordx4 v[172:175], v[30:31], off
	v_lshl_add_u64 v[26:27], s[0:1], 0, v[28:29]
	v_lshl_add_u64 v[26:27], v[26:27], 0, v[186:187]
	v_lshl_add_u64 v[2:3], s[0:1], 0, v[2:3]
	v_lshl_add_u64 v[2:3], v[2:3], 0, v[186:187]
	global_load_dwordx4 v[168:171], v[26:27], off
	global_load_dwordx4 v[176:179], v[2:3], off
	s_movk_i32 s0, 0x190
	v_mul_lo_u32 v200, v0, s0
	v_mul_lo_u32 v210, v199, s0
	s_movk_i32 s0, 0xffb0
	v_lshlrev_b64 v[26:27], 10, v[0:1]
	v_add3_u32 v1, 0, v200, v186
	v_add3_u32 v2, 0, v210, v188
	v_mul_lo_u32 v211, v0, s12
	v_mul_lo_u32 v0, v0, s0
	s_movk_i32 s0, 0x3200
	v_lshlrev_b32_e32 v183, 2, v107
	s_add_u32 s4, s90, s6
	v_lshlrev_b32_e32 v28, 3, v32
	v_lshlrev_b64 v[30:31], 10, v[4:5]
	s_addc_u32 s15, s91, s7
	v_xor_b32_e32 v64, 0x80000000, v33
	s_add_u32 s6, s92, s6
	v_mov_b32_e32 v3, v181
	v_mov_b32_e32 v4, v181
	v_mov_b32_e32 v5, v181
	v_lshlrev_b64 v[192:193], 1, v[26:27]
	v_lshlrev_b64 v[194:195], 1, v[30:31]
	v_add_u32_e32 v201, 0x3200, v200
	v_add_u32_e32 v212, 0x2800, v211
	v_mov_b32_e32 v65, v64
	v_mov_b32_e32 v66, v64
	v_mov_b32_e32 v67, v64
	v_mov_b32_e32 v68, v64
	v_mov_b32_e32 v69, v64
	v_mov_b32_e32 v70, v64
	v_mov_b32_e32 v71, v64
	v_mov_b32_e32 v72, v64
	v_mov_b32_e32 v73, v64
	v_mov_b32_e32 v74, v64
	v_mov_b32_e32 v75, v64
	v_mov_b32_e32 v76, v64
	v_mov_b32_e32 v77, v64
	v_mov_b32_e32 v78, v64
	v_mov_b32_e32 v79, v64
	v_lshl_add_u64 v[190:191], s[86:87], 0, v[188:189]
	s_waitcnt vmcnt(9)
	ds_write_b128 v1, v[214:217]
	s_waitcnt vmcnt(8)
	ds_write_b128 v1, v[218:221] offset:12800
	v_mov_b32_e32 v6, v181
	v_mov_b32_e32 v7, v181
	v_mov_b32_e32 v8, v181
	v_mov_b32_e32 v9, v181
	v_mov_b32_e32 v10, v181
	v_mov_b32_e32 v11, v181
	v_mov_b32_e32 v12, v181
	v_mov_b32_e32 v13, v181
	s_addc_u32 s7, s93, s7
	s_or_b32 s13, s13, 0xc0
	v_mov_b32_e32 v187, 0
	s_waitcnt vmcnt(7)
	ds_write_b128 v2, v[222:225] offset:256
	v_add_u32_e32 v2, v1, v0
	v_add3_u32 v0, v1, s0, v0
	s_waitcnt vmcnt(6)
	ds_write_b128 v0, v[226:229] offset:48640
	v_mul_u32_u24_e32 v0, 0x190, v108
	v_add3_u32 v213, 0, v0, v180
	v_lshrrev_b32_e32 v0, 2, v106
	v_and_or_b32 v0, v0, 3, v183
	v_lshlrev_b32_e32 v1, 1, v106
	v_mad_u32_u24 v0, v0, s12, 0
	v_and_b32_e32 v1, 32, v1
	s_waitcnt vmcnt(5)
	ds_write_b128 v2, v[230:233] offset:51200
	v_lshlrev_b32_e32 v2, 3, v106
	v_and_b32_e32 v2, 24, v2
	v_mov_b32_e32 v14, v181
	v_mov_b32_e32 v15, v181
	v_add3_u32 v198, v0, v1, v2
	v_mov_b32_e32 v0, v181
	v_mov_b32_e32 v1, v181
	v_mov_b32_e32 v2, v181
	v_lshlrev_b32_e32 v180, 1, v28
	v_mov_b64_e32 v[30:31], v[14:15]
	v_mov_b64_e32 v[46:47], v[14:15]
	v_mov_b64_e32 v[62:63], v[14:15]
	v_mov_b64_e32 v[28:29], v[12:13]
	v_mov_b64_e32 v[26:27], v[10:11]
	v_mov_b64_e32 v[24:25], v[8:9]
	v_mov_b64_e32 v[22:23], v[6:7]
	v_mov_b64_e32 v[20:21], v[4:5]
	v_mov_b64_e32 v[18:19], v[2:3]
	v_mov_b64_e32 v[16:17], v[0:1]
	v_mov_b64_e32 v[44:45], v[12:13]
	v_mov_b64_e32 v[42:43], v[10:11]
	v_mov_b64_e32 v[40:41], v[8:9]
	v_mov_b64_e32 v[38:39], v[6:7]
	v_mov_b64_e32 v[36:37], v[4:5]
	v_mov_b64_e32 v[34:35], v[2:3]
	v_mov_b64_e32 v[32:33], v[0:1]
	v_mov_b64_e32 v[60:61], v[12:13]
	v_mov_b64_e32 v[58:59], v[10:11]
	v_mov_b64_e32 v[56:57], v[8:9]
	v_mov_b64_e32 v[54:55], v[6:7]
	v_mov_b64_e32 v[52:53], v[4:5]
	v_mov_b64_e32 v[50:51], v[2:3]
	v_mov_b64_e32 v[48:49], v[0:1]
	s_waitcnt lgkmcnt(0)
	s_barrier
	s_cmp_lt_u32 s23, 0x80
	s_cbranch_scc1 .Lprio_mla
	s_setprio 1
; template <int DQK, bool MOBA>
; __device__ __forceinline__ void attn_unit(const Args& A, int b, int h, int qb, lptr lds) {
;     ...
;     for (int t = 0; t < NT; ++t) {
;         const int buf = t & 1;
;         if (t + 1 < NT) { ATT_WRITE(buf ^ 1); if (t + 2 < NT) ATT_LOAD(t + 2); }
.Lprio_mla:
	s_branch .LBB0_812
.LBB0_810:
	s_xor_b32 s0, s44, 1
	s_mul_i32 s1, s0, 0x6400
	s_mul_i32 s0, s0, 0x5000
	v_add3_u32 v246, s1, v200, v186
	s_waitcnt vmcnt(0)
	ds_write_b128 v246, v[176:179]
	v_add3_u32 v246, s1, v201, v186
	ds_write_b128 v246, v[168:171]
	v_add3_u32 v246, s1, v210, v188
	ds_write_b128 v246, v[172:175] offset:256
	v_add3_u32 v246, s0, v211, v186
	ds_write_b128 v246, v[164:167] offset:51200
	v_add3_u32 v246, s0, v212, v186
	ds_write_b128 v246, v[160:163] offset:51200
	s_cmp_ge_u32 s5, s26
	s_cbranch_scc1 .Lmla_hd_done_a
	s_add_i32 s0, s25, s5
	s_add_i32 s1, s5, -4
	s_cmp_lt_u32 s45, 2
	s_cselect_b32 s0, s0, s1
	s_lshl_b32 s0, s0, 6
	s_add_i32 s0, s0, s24
	s_ashr_i32 s1, s0, 31
	s_lshl_b64 s[46:47], s[0:1], 11
	s_add_u32 s48, s4, s46
	s_addc_u32 s49, s15, s47
	v_lshl_add_u64 v[248:249], s[48:49], 0, v[192:193]
	v_lshl_add_u64 v[248:249], v[248:249], 0, v[180:181]
	v_lshl_add_u64 v[250:251], s[48:49], 0, v[194:195]
	v_lshl_add_u64 v[250:251], v[250:251], 0, v[180:181]
	global_load_dwordx4 v[176:179], v[248:249], off
	global_load_dwordx4 v[168:171], v[250:251], off
	v_add_u32_e32 v248, s0, v199
	v_ashrrev_i32_e32 v249, 31, v248
	s_add_u32 s0, s6, s46
	v_lshlrev_b64 v[248:249], 7, v[248:249]
	s_addc_u32 s1, s7, s47
	v_lshl_add_u64 v[248:249], v[190:191], 0, v[248:249]
	v_lshl_add_u64 v[250:251], s[0:1], 0, v[192:193]
	v_lshl_add_u64 v[250:251], v[250:251], 0, v[180:181]
	global_load_dwordx4 v[172:175], v[248:249], off
	global_load_dwordx4 v[164:167], v[250:251], off
	v_lshl_add_u64 v[248:249], s[0:1], 0, v[194:195]
	v_lshl_add_u64 v[248:249], v[248:249], 0, v[180:181]
	global_load_dwordx4 v[160:163], v[248:249], off
